# all seven GEMM K-loops restructured (DMA interleaved with MFMAs, SALU m0, counted lgkmcnt), dedicated address temp per loop
# speedup vs baseline: 1.0095x; 1.0031x over previous
; #define MFMA(a, b, c) __builtin_amdgcn_mfma_f32_32x32x16_bf16((a), (b), (c), 0, 0, 0)
; #define DSR(dst, addr, off) asm volatile("ds_read_b128 %0, %1 offset:" #off : "=&v"(dst) : "v"(addr))
; template <bool VT>
; DI void g_compute_asm(unsigned aA0, unsigned aA1, unsigned aB0, unsigned aB1, f32x16 (&acc)[4][2]) {
;   bf16x8 a0[4], a1[4], b0[2], b1[2];
;   DSR(b0[0], aB0, 0); DSR(b0[1], aB0, 2048);
;   DSR(a0[0], aA0, 0); DSR(a0[1], aA0, 2048); DSR(a0[2], aA0, 4096); DSR(a0[3], aA0, 6144);
;   DSR(b1[0], aB1, 0); DSR(b1[1], aB1, 2048);
;   DSR(a1[0], aA1, 0); DSR(a1[1], aA1, 2048); DSR(a1[2], aA1, 4096); DSR(a1[3], aA1, 6144);
;   asm volatile("s_waitcnt lgkmcnt(6)" : "+v"(b0[0]), "+v"(b0[1]), "+v"(a0[0]), "+v"(a0[1]), "+v"(a0[2]), "+v"(a0[3]));
; #pragma unroll
;   for (int mi = 0; mi < 4; ++mi)
; #pragma unroll
;     for (int ni = 0; ni < 2; ++ni) {
;       if (VT) acc[mi][ni] = MFMA(a0[mi], b0[ni], acc[mi][ni]);
;       else acc[mi][ni] = MFMA(b0[ni], a0[mi], acc[mi][ni]);
;     }
;   __builtin_amdgcn_sched_barrier(0);
;   asm volatile("s_waitcnt lgkmcnt(0)" : "+v"(b1[0]), "+v"(b1[1]), "+v"(a1[0]), "+v"(a1[1]), "+v"(a1[2]), "+v"(a1[3]));
; #pragma unroll
;   for (int mi = 0; mi < 4; ++mi)
; #pragma unroll
;     for (int ni = 0; ni < 2; ++ni) {
;       if (VT) acc[mi][ni] = MFMA(a1[mi], b1[ni], acc[mi][ni]);
;       else acc[mi][ni] = MFMA(b1[ni], a1[mi], acc[mi][ni]);
;     }
; }
; template <bool VT>
; DI int gemm_kloop(const bf16_t* Ag, size_t lda, const bf16_t* Bg, size_t ldb, int nk, bf16_t* ring, f32x16 (&acc)[4][2], int tid, int wm, int wn,
;                   int r, int h, int st0, bool pre, const bf16_t* AgN, const bf16_t* BgN) {
;     ...
;   for (int kt = 0; kt < nk - 1; ++kt) {
;     asm volatile("s_waitcnt vmcnt(6)" ::: "memory");
;     __builtin_amdgcn_s_barrier();
;     if (kt + 2 < nk) dma_issue(Ag, lda, Bg, ldb, kt + 2, ring + (st == 0 ? 2 : st - 1) * STG, wid, lane);
;     const unsigned so = (unsigned)st * (unsigned)(STG * 2);
;     g_compute_asm<VT>(oA0 + so, oA1 + so, oB0 + so, oB1 + so, acc);
;     st = st == 2 ? 0 : st + 1;
.LBB0_200:
	v_mul_lo_u32 v32, v162, s95
	v_readfirstlane_b32 s44, v162
	v_lshl_add_u64 v[168:169], v[150:151], 0, s[24:25]
	s_mul_i32 s98, s44, 0x3000
	s_addk_i32 s98, 0xd000
	s_cmp_lg_u32 s44, 0
	s_cselect_b32 s98, s98, 0x6000
	s_lshl_b32 s98, s98, 1
	s_add_u32 s98, s98, s99
	s_mul_i32 s44, s44, 0x6000
	v_add_u32_e32 v176, s44, v160
	v_add_u32_e32 v167, s44, v158
	v_add_u32_e32 v32, s44, v161
	v_add_u32_e32 v239, s44, v159
	s_mov_b32 m0, s98
	s_waitcnt vmcnt(6)
	s_barrier
	global_load_lds_dwordx4 v[168:169], off
	ds_read_b128 v[168:171], v176 offset:0
	ds_read_b128 v[172:175], v176 offset:2048
	ds_read_b128 v[176:179], v167 offset:0
	ds_read_b128 v[180:183], v167 offset:2048
	ds_read_b128 v[184:187], v167 offset:4096
	ds_read_b128 v[188:191], v167 offset:6144
	ds_read_b128 v[192:195], v32 offset:0
	ds_read_b128 v[196:199], v32 offset:2048
	ds_read_b128 v[200:203], v239 offset:0
	ds_read_b128 v[204:207], v239 offset:2048
	ds_read_b128 v[244:247], v239 offset:4096
	ds_read_b128 v[248:251], v239 offset:6144
	s_waitcnt lgkmcnt(9)
	v_mfma_f32_32x32x16_bf16 v[114:129], v[168:171], v[176:179], v[114:129]
	v_mfma_f32_32x32x16_bf16 v[98:113], v[172:175], v[176:179], v[98:113]
	s_add_u32 m0, s98, 0x1000
	v_lshl_add_u64 v[216:217], v[148:149], 0, s[24:25]
	global_load_lds_dwordx4 v[216:217], off
	s_waitcnt lgkmcnt(8)
	v_mfma_f32_32x32x16_bf16 v[82:97], v[168:171], v[180:183], v[82:97]
	v_mfma_f32_32x32x16_bf16 v[66:81], v[172:175], v[180:183], v[66:81]
	s_add_u32 m0, s98, 0x2000
	v_lshl_add_u64 v[216:217], v[146:147], 0, s[24:25]
	global_load_lds_dwordx4 v[216:217], off
	s_waitcnt lgkmcnt(7)
	v_mfma_f32_32x32x16_bf16 v[50:65], v[168:171], v[184:187], v[50:65]
	v_mfma_f32_32x32x16_bf16 v[34:49], v[172:175], v[184:187], v[34:49]
	s_add_u32 m0, s98, 0x3000
	v_lshl_add_u64 v[216:217], v[144:145], 0, s[24:25]
	global_load_lds_dwordx4 v[216:217], off
	s_waitcnt lgkmcnt(6)
	v_mfma_f32_32x32x16_bf16 v[16:31], v[168:171], v[188:191], v[16:31]
	v_mfma_f32_32x32x16_bf16 v[0:15], v[172:175], v[188:191], v[0:15]
	s_add_u32 m0, s98, 0x4000
	v_lshl_add_u64 v[216:217], v[142:143], 0, s[24:25]
	global_load_lds_dwordx4 v[216:217], off
	s_waitcnt lgkmcnt(3)
	v_mfma_f32_32x32x16_bf16 v[114:129], v[192:195], v[200:203], v[114:129]
	v_mfma_f32_32x32x16_bf16 v[98:113], v[196:199], v[200:203], v[98:113]
	s_add_u32 m0, s98, 0x5000
	v_lshl_add_u64 v[216:217], v[140:141], 0, s[24:25]
	global_load_lds_dwordx4 v[216:217], off
	s_add_u32 s24, s24, 64
	v_add_u32_e32 v32, 1, v162
	v_cmp_ne_u32_e32 vcc, 2, v162
	s_addc_u32 s25, s25, 0
	s_cmpk_eq_i32 s24, 0x780
	v_cndmask_b32_e32 v162, 0, v32, vcc
	s_waitcnt lgkmcnt(2)
	v_mfma_f32_32x32x16_bf16 v[82:97], v[192:195], v[204:207], v[82:97]
	v_mfma_f32_32x32x16_bf16 v[66:81], v[196:199], v[204:207], v[66:81]
	s_waitcnt lgkmcnt(1)
	v_mfma_f32_32x32x16_bf16 v[50:65], v[192:195], v[244:247], v[50:65]
	v_mfma_f32_32x32x16_bf16 v[34:49], v[196:199], v[244:247], v[34:49]
	s_waitcnt lgkmcnt(0)
	v_mfma_f32_32x32x16_bf16 v[16:31], v[192:195], v[248:251], v[16:31]
	v_mfma_f32_32x32x16_bf16 v[0:15], v[196:199], v[248:251], v[0:15]
	s_cbranch_scc0 .LBB0_200
	v_mov_b32_e32 v216, 0x100
	v_mov_b32_e32 v217, 0x200
	v_mul_lo_u32 v32, v162, s84
	v_add_u32_e32 v148, v32, v160
	s_waitcnt vmcnt(6)
	s_barrier
; DI void dma_issue(const bf16_t* Ag, size_t lda, const bf16_t* Bg, size_t ldb, int kt, bf16_t* stage, int wid, int lane) {
;   const int rl = lane >> 2, c = (lane & 3) ^ ((lane >> 4) & 3);
; #pragma unroll
;   for (int i = 0; i < 4; ++i) {
;     const int j = wid + 4 * i;
;     __builtin_amdgcn_global_load_lds((const unsigned*)(Ag + (size_t)(16 * j + rl) * lda + kt * 32 + c * 8), (unsigned*)(stage + j * 512), 16, 0, 0);
;   }
; #pragma unroll
;   for (int i = 0; i < 2; ++i) {
;     const int j = wid + 4 * i;
;     __builtin_amdgcn_global_load_lds((const unsigned*)(Bg + (size_t)(16 * j + rl) * ldb + kt * 32 + c * 8), (unsigned*)(stage + STG_A + j * 512), 16, 0, 0);
;   }
; }
; template <bool VT>
; DI int gemm_kloop(const bf16_t* Ag, size_t lda, const bf16_t* Bg, size_t ldb, int nk, bf16_t* ring, f32x16 (&acc)[4][2], int tid, int wm, int wn,
;                   int r, int h, int st0, bool pre, const bf16_t* AgN, const bf16_t* BgN) {
;     ...
;   }
;   asm volatile("s_waitcnt vmcnt(0)" ::: "memory");
;   __builtin_amdgcn_s_barrier();
;   if (AgN) {
;     const int s1 = st == 2 ? 0 : st + 1, s2 = s1 == 2 ? 0 : s1 + 1;
;     dma_issue(AgN, lda, BgN, ldb, 0, ring + s1 * STG, wid, lane);
;     dma_issue(AgN, lda, BgN, ldb, 1, ring + s2 * STG, wid, lane);
;   }
;   {
;     const unsigned so = (unsigned)st * (unsigned)(STG * 2);
;     g_compute_asm<VT>(oA0 + so, oA1 + so, oB0 + so, oB1 + so, acc);
	v_add_u32_e32 v167, v32, v158
	ds_read_b128 v[140:143], v148 offset:0
	ds_read_b128 v[144:147], v148 offset:2048
	ds_read_b128 v[148:151], v167 offset:0
	ds_read_b128 v[168:171], v167 offset:2048
	ds_read_b128 v[172:175], v167 offset:4096
	ds_read_b128 v[176:179], v167 offset:6144
	v_add_u32_e32 v204, v32, v159
	v_add_u32_e32 v32, v32, v161
	ds_read_b128 v[180:183], v32 offset:0
	ds_read_b128 v[184:187], v32 offset:2048
	ds_read_b128 v[188:191], v204 offset:0
	ds_read_b128 v[192:195], v204 offset:2048
	ds_read_b128 v[196:199], v204 offset:4096
	ds_read_b128 v[200:203], v204 offset:6144
	s_waitcnt lgkmcnt(6)
	s_nop 0
	v_mfma_f32_32x32x16_bf16 v[114:129], v[140:143], v[148:151], v[114:129]
	v_mfma_f32_32x32x16_bf16 v[98:113], v[144:147], v[148:151], v[98:113]
	v_mfma_f32_32x32x16_bf16 v[82:97], v[140:143], v[168:171], v[82:97]
	v_mfma_f32_32x32x16_bf16 v[66:81], v[144:147], v[168:171], v[66:81]
	v_mfma_f32_32x32x16_bf16 v[50:65], v[140:143], v[172:175], v[50:65]
	v_mfma_f32_32x32x16_bf16 v[34:49], v[144:147], v[172:175], v[34:49]
	v_mfma_f32_32x32x16_bf16 v[16:31], v[140:143], v[176:179], v[16:31]
	v_mfma_f32_32x32x16_bf16 v[0:15], v[144:147], v[176:179], v[0:15]
	s_waitcnt lgkmcnt(0)
	s_waitcnt vmcnt(0)
	v_add_u32_e32 v32, 1, v162
	v_mfma_f32_32x32x16_bf16 v[114:129], v[180:183], v[188:191], v[114:129]
	v_cmp_ne_u32_e32 vcc, 2, v162
	s_cmp_lg_u64 s[12:13], 0
	s_barrier
	v_cndmask_b32_e32 v140, 0, v32, vcc
	v_mfma_f32_32x32x16_bf16 v[98:113], v[184:187], v[188:191], v[98:113]
	v_mfma_f32_32x32x16_bf16 v[82:97], v[180:183], v[192:195], v[82:97]
	v_mfma_f32_32x32x16_bf16 v[66:81], v[184:187], v[192:195], v[66:81]
	v_mfma_f32_32x32x16_bf16 v[50:65], v[180:183], v[196:199], v[50:65]
	v_mfma_f32_32x32x16_bf16 v[34:49], v[184:187], v[196:199], v[34:49]
	v_mfma_f32_32x32x16_bf16 v[16:31], v[180:183], v[200:203], v[16:31]
	v_mfma_f32_32x32x16_bf16 v[0:15], v[184:187], v[200:203], v[0:15]
	s_cbranch_scc0 .LBB0_203
	v_add_u32_e32 v32, 1, v140
	v_cmp_ne_u32_e32 vcc, 2, v140
	v_lshlrev_b32_e32 v149, 1, v163
	v_lshlrev_b32_e32 v151, 1, v164
	v_cndmask_b32_e32 v32, 0, v32, vcc
	v_mul_lo_u32 v141, v32, s95
	v_lshlrev_b32_e32 v148, 1, v141
	v_add_u32_e32 v150, v148, v149
	v_lshl_add_u64 v[142:143], s[12:13], 0, v[138:139]
	v_lshlrev_b64 v[130:131], 1, v[130:131]
	v_readfirstlane_b32 s24, v150
	v_add_u32_e32 v162, v148, v151
	v_lshl_add_u64 v[144:145], v[142:143], 0, v[130:131]
	s_mov_b32 m0, s24
	v_lshlrev_b64 v[132:133], 1, v[132:133]
	v_readfirstlane_b32 s24, v162
	v_add_u32_e32 v163, v148, v166
	global_load_lds_dwordx4 v[144:145], off
	v_lshl_add_u64 v[146:147], v[142:143], 0, v[132:133]
	s_mov_b32 m0, s24
	v_lshl_add_u64 v[134:135], v[134:135], 1, v[142:143]
	v_readfirstlane_b32 s24, v163
	v_lshl_add_u64 v[136:137], v[136:137], 1, v[142:143]
	v_add_u32_e32 v142, v148, v165
	global_load_lds_dwordx4 v[146:147], off
	s_mov_b32 m0, s24
	v_readfirstlane_b32 s24, v142
	v_lshl_add_u64 v[138:139], s[14:15], 0, v[138:139]
	v_add_u32_e32 v142, 0x4000, v150
	global_load_lds_dwordx4 v[134:135], off
	s_mov_b32 m0, s24
	v_lshl_add_u64 v[130:131], v[138:139], 0, v[130:131]
	v_readfirstlane_b32 s24, v142
	v_lshl_add_u64 v[132:133], v[138:139], 0, v[132:133]
	v_add_u32_e32 v138, 0x4000, v162
	global_load_lds_dwordx4 v[136:137], off
	s_mov_b32 m0, s24
	v_readfirstlane_b32 s24, v138
	v_add_u32_e32 v138, 0x3000, v141
	v_cmp_ne_u32_e32 vcc, 2, v32
	global_load_lds_dwordx4 v[130:131], off
	s_nop 0
	v_cndmask_b32_e32 v32, 0, v138, vcc
	v_lshlrev_b32_e32 v32, 1, v32
	v_add_u32_e32 v141, v32, v149
	s_mov_b32 m0, s24
	v_readfirstlane_b32 s24, v141
	v_add_u32_e32 v142, v32, v151
	global_load_lds_dwordx4 v[132:133], off
	v_lshl_add_u64 v[138:139], v[144:145], 0, 64
	s_mov_b32 m0, s24
	v_readfirstlane_b32 s24, v142
	global_load_lds_dwordx4 v[138:139], off
	v_lshl_add_u64 v[138:139], v[146:147], 0, 64
	s_mov_b32 m0, s24
	v_lshl_add_u64 v[134:135], v[134:135], 0, 64
	global_load_lds_dwordx4 v[138:139], off
	v_add_u32_e32 v138, v32, v166
	v_add_u32_e32 v32, v32, v165
	v_readfirstlane_b32 s24, v138
	s_mov_b32 m0, s24
	v_readfirstlane_b32 s24, v32
	v_add_u32_e32 v32, 0x4000, v141
	global_load_lds_dwordx4 v[134:135], off
	v_lshl_add_u64 v[134:135], v[136:137], 0, 64
	s_mov_b32 m0, s24
	v_readfirstlane_b32 s24, v32
	v_add_u32_e32 v32, 0x4000, v142
	global_load_lds_dwordx4 v[134:135], off
	v_lshl_add_u64 v[130:131], v[130:131], 0, 64
	s_mov_b32 m0, s24
	v_readfirstlane_b32 s24, v32
	global_load_lds_dwordx4 v[130:131], off
	v_lshl_add_u64 v[130:131], v[132:133], 0, 64
	s_mov_b32 m0, s24
	s_nop 0
	global_load_lds_dwordx4 v[130:131], off

; #define MFMA(a, b, c) __builtin_amdgcn_mfma_f32_32x32x16_bf16((a), (b), (c), 0, 0, 0)
; #define DSR(dst, addr, off) asm volatile("ds_read_b128 %0, %1 offset:" #off : "=&v"(dst) : "v"(addr))
; template <bool VT>
; DI void g_compute_asm(unsigned aA0, unsigned aA1, unsigned aB0, unsigned aB1, f32x16 (&acc)[4][2]) {
;   bf16x8 a0[4], a1[4], b0[2], b1[2];
;   DSR(b0[0], aB0, 0); DSR(b0[1], aB0, 2048);
;   DSR(a0[0], aA0, 0); DSR(a0[1], aA0, 2048); DSR(a0[2], aA0, 4096); DSR(a0[3], aA0, 6144);
;   DSR(b1[0], aB1, 0); DSR(b1[1], aB1, 2048);
;   DSR(a1[0], aA1, 0); DSR(a1[1], aA1, 2048); DSR(a1[2], aA1, 4096); DSR(a1[3], aA1, 6144);
;   asm volatile("s_waitcnt lgkmcnt(6)" : "+v"(b0[0]), "+v"(b0[1]), "+v"(a0[0]), "+v"(a0[1]), "+v"(a0[2]), "+v"(a0[3]));
; #pragma unroll
;   for (int mi = 0; mi < 4; ++mi)
; #pragma unroll
;     for (int ni = 0; ni < 2; ++ni) {
;       if (VT) acc[mi][ni] = MFMA(a0[mi], b0[ni], acc[mi][ni]);
;       else acc[mi][ni] = MFMA(b0[ni], a0[mi], acc[mi][ni]);
;     }
;   __builtin_amdgcn_sched_barrier(0);
;   asm volatile("s_waitcnt lgkmcnt(0)" : "+v"(b1[0]), "+v"(b1[1]), "+v"(a1[0]), "+v"(a1[1]), "+v"(a1[2]), "+v"(a1[3]));
; #pragma unroll
;   for (int mi = 0; mi < 4; ++mi)
; #pragma unroll
;     for (int ni = 0; ni < 2; ++ni) {
;       if (VT) acc[mi][ni] = MFMA(a1[mi], b1[ni], acc[mi][ni]);
;       else acc[mi][ni] = MFMA(b1[ni], a1[mi], acc[mi][ni]);
;     }
; }
; template <bool VT>
; DI int gemm_kloop(const bf16_t* Ag, size_t lda, const bf16_t* Bg, size_t ldb, int nk, bf16_t* ring, f32x16 (&acc)[4][2], int tid, int wm, int wn,
;                   int r, int h, int st0, bool pre, const bf16_t* AgN, const bf16_t* BgN) {
;     ...
;   for (int kt = 0; kt < nk - 1; ++kt) {
;     asm volatile("s_waitcnt vmcnt(6)" ::: "memory");
;     __builtin_amdgcn_s_barrier();
;     if (kt + 2 < nk) dma_issue(Ag, lda, Bg, ldb, kt + 2, ring + (st == 0 ? 2 : st - 1) * STG, wid, lane);
;     const unsigned so = (unsigned)st * (unsigned)(STG * 2);
;     g_compute_asm<VT>(oA0 + so, oA1 + so, oB0 + so, oB1 + so, acc);
;     st = st == 2 ? 0 : st + 1;
.LBB0_210:
	v_mul_lo_u32 v32, v162, s95
	v_readfirstlane_b32 s18, v162
	v_lshl_add_u64 v[168:169], v[150:151], 0, s[16:17]
	s_mul_i32 s98, s18, 0x3000
	s_addk_i32 s98, 0xd000
	s_cmp_lg_u32 s18, 0
	s_cselect_b32 s98, s98, 0x6000
	s_lshl_b32 s98, s98, 1
	s_add_u32 s98, s98, s99
	s_mul_i32 s18, s18, 0x6000
	v_add_u32_e32 v176, s18, v160
	v_add_u32_e32 v167, s18, v158
	v_add_u32_e32 v32, s18, v161
	v_add_u32_e32 v239, s18, v159
	s_mov_b32 m0, s98
	s_waitcnt vmcnt(6)
	s_barrier
	global_load_lds_dwordx4 v[168:169], off
	ds_read_b128 v[168:171], v176 offset:0
	ds_read_b128 v[172:175], v176 offset:2048
	ds_read_b128 v[176:179], v167 offset:0
	ds_read_b128 v[180:183], v167 offset:2048
	ds_read_b128 v[184:187], v167 offset:4096
	ds_read_b128 v[188:191], v167 offset:6144
	ds_read_b128 v[192:195], v32 offset:0
	ds_read_b128 v[196:199], v32 offset:2048
	ds_read_b128 v[204:207], v239 offset:0
	ds_read_b128 v[244:247], v239 offset:2048
	ds_read_b128 v[248:251], v239 offset:4096
	ds_read_b128 v[200:203], v239 offset:6144
	s_waitcnt lgkmcnt(9)
	v_mfma_f32_32x32x16_bf16 v[114:129], v[176:179], v[168:171], v[114:129]
	v_mfma_f32_32x32x16_bf16 v[98:113], v[176:179], v[172:175], v[98:113]
	s_add_u32 m0, s98, 0x1000
	v_lshl_add_u64 v[216:217], v[148:149], 0, s[16:17]
	global_load_lds_dwordx4 v[216:217], off
	s_waitcnt lgkmcnt(8)
	v_mfma_f32_32x32x16_bf16 v[82:97], v[180:183], v[168:171], v[82:97]
	v_mfma_f32_32x32x16_bf16 v[66:81], v[180:183], v[172:175], v[66:81]
	s_add_u32 m0, s98, 0x2000
	v_lshl_add_u64 v[216:217], v[146:147], 0, s[16:17]
	global_load_lds_dwordx4 v[216:217], off
	s_waitcnt lgkmcnt(7)
	v_mfma_f32_32x32x16_bf16 v[50:65], v[184:187], v[168:171], v[50:65]
	v_mfma_f32_32x32x16_bf16 v[34:49], v[184:187], v[172:175], v[34:49]
	s_add_u32 m0, s98, 0x3000
	v_lshl_add_u64 v[216:217], v[144:145], 0, s[16:17]
	global_load_lds_dwordx4 v[216:217], off
	s_waitcnt lgkmcnt(6)
	v_mfma_f32_32x32x16_bf16 v[16:31], v[188:191], v[168:171], v[16:31]
	v_mfma_f32_32x32x16_bf16 v[0:15], v[188:191], v[172:175], v[0:15]
	s_add_u32 m0, s98, 0x4000
	v_lshl_add_u64 v[216:217], v[142:143], 0, s[16:17]
	global_load_lds_dwordx4 v[216:217], off
	s_waitcnt lgkmcnt(3)
	v_mfma_f32_32x32x16_bf16 v[114:129], v[204:207], v[192:195], v[114:129]
	v_mfma_f32_32x32x16_bf16 v[98:113], v[204:207], v[196:199], v[98:113]
	s_add_u32 m0, s98, 0x5000
	v_lshl_add_u64 v[216:217], v[140:141], 0, s[16:17]
	global_load_lds_dwordx4 v[216:217], off
	s_add_u32 s16, s16, 64
	v_add_u32_e32 v32, 1, v162
	v_cmp_ne_u32_e32 vcc, 2, v162
	s_addc_u32 s17, s17, 0
	s_cmpk_eq_i32 s16, 0x780
	v_cndmask_b32_e32 v162, 0, v32, vcc
	s_waitcnt lgkmcnt(2)
	v_mfma_f32_32x32x16_bf16 v[82:97], v[244:247], v[192:195], v[82:97]
	v_mfma_f32_32x32x16_bf16 v[66:81], v[244:247], v[196:199], v[66:81]
	s_waitcnt lgkmcnt(1)
	v_mfma_f32_32x32x16_bf16 v[50:65], v[248:251], v[192:195], v[50:65]
	v_mfma_f32_32x32x16_bf16 v[34:49], v[248:251], v[196:199], v[34:49]
	s_waitcnt lgkmcnt(0)
	v_mfma_f32_32x32x16_bf16 v[16:31], v[200:203], v[192:195], v[16:31]
	v_mfma_f32_32x32x16_bf16 v[0:15], v[200:203], v[196:199], v[0:15]
	s_cbranch_scc0 .LBB0_210
	v_mov_b32_e32 v216, 0x100
	v_mov_b32_e32 v217, 0x200
	v_mul_lo_u32 v32, v162, s84
	v_add_u32_e32 v148, v32, v160
	s_waitcnt vmcnt(6)
	s_barrier
; DI void dma_issue(const bf16_t* Ag, size_t lda, const bf16_t* Bg, size_t ldb, int kt, bf16_t* stage, int wid, int lane) {
;   const int rl = lane >> 2, c = (lane & 3) ^ ((lane >> 4) & 3);
; #pragma unroll
;   for (int i = 0; i < 4; ++i) {
;     const int j = wid + 4 * i;
;     __builtin_amdgcn_global_load_lds((const unsigned*)(Ag + (size_t)(16 * j + rl) * lda + kt * 32 + c * 8), (unsigned*)(stage + j * 512), 16, 0, 0);
;   }
; #pragma unroll
;   for (int i = 0; i < 2; ++i) {
;     const int j = wid + 4 * i;
;     __builtin_amdgcn_global_load_lds((const unsigned*)(Bg + (size_t)(16 * j + rl) * ldb + kt * 32 + c * 8), (unsigned*)(stage + STG_A + j * 512), 16, 0, 0);
;   }
; }
; template <bool VT>
; DI int gemm_kloop(const bf16_t* Ag, size_t lda, const bf16_t* Bg, size_t ldb, int nk, bf16_t* ring, f32x16 (&acc)[4][2], int tid, int wm, int wn,
;                   int r, int h, int st0, bool pre, const bf16_t* AgN, const bf16_t* BgN) {
;     ...
;   }
;   asm volatile("s_waitcnt vmcnt(0)" ::: "memory");
;   __builtin_amdgcn_s_barrier();
;   if (AgN) {
;     const int s1 = st == 2 ? 0 : st + 1, s2 = s1 == 2 ? 0 : s1 + 1;
;     dma_issue(AgN, lda, BgN, ldb, 0, ring + s1 * STG, wid, lane);
;     dma_issue(AgN, lda, BgN, ldb, 1, ring + s2 * STG, wid, lane);
;   }
;   {
;     const unsigned so = (unsigned)st * (unsigned)(STG * 2);
;     g_compute_asm<VT>(oA0 + so, oA1 + so, oB0 + so, oB1 + so, acc);
	v_add_u32_e32 v167, v32, v158
	ds_read_b128 v[140:143], v148 offset:0
	ds_read_b128 v[144:147], v148 offset:2048
	ds_read_b128 v[148:151], v167 offset:0
	ds_read_b128 v[168:171], v167 offset:2048
	ds_read_b128 v[172:175], v167 offset:4096
	ds_read_b128 v[176:179], v167 offset:6144
	v_add_u32_e32 v200, v32, v159
	v_add_u32_e32 v32, v32, v161
	ds_read_b128 v[180:183], v32 offset:0
	ds_read_b128 v[184:187], v32 offset:2048
	ds_read_b128 v[188:191], v200 offset:0
	ds_read_b128 v[192:195], v200 offset:2048
	ds_read_b128 v[196:199], v200 offset:4096
	ds_read_b128 v[204:207], v200 offset:6144
	s_waitcnt lgkmcnt(6)
	s_nop 0
	v_mfma_f32_32x32x16_bf16 v[114:129], v[148:151], v[140:143], v[114:129]
	v_mfma_f32_32x32x16_bf16 v[98:113], v[148:151], v[144:147], v[98:113]
	v_mfma_f32_32x32x16_bf16 v[82:97], v[168:171], v[140:143], v[82:97]
	v_mfma_f32_32x32x16_bf16 v[66:81], v[168:171], v[144:147], v[66:81]
	v_mfma_f32_32x32x16_bf16 v[50:65], v[172:175], v[140:143], v[50:65]
	v_mfma_f32_32x32x16_bf16 v[34:49], v[172:175], v[144:147], v[34:49]
	v_mfma_f32_32x32x16_bf16 v[16:31], v[176:179], v[140:143], v[16:31]
	v_mfma_f32_32x32x16_bf16 v[0:15], v[176:179], v[144:147], v[0:15]
	s_waitcnt lgkmcnt(0)
	s_waitcnt vmcnt(0)
	v_add_u32_e32 v32, 1, v162
	v_mfma_f32_32x32x16_bf16 v[114:129], v[188:191], v[180:183], v[114:129]
	v_cmp_ne_u32_e32 vcc, 2, v162
	s_cmp_lg_u64 s[12:13], 0
	s_barrier
	v_cndmask_b32_e32 v140, 0, v32, vcc
	v_mfma_f32_32x32x16_bf16 v[98:113], v[188:191], v[184:187], v[98:113]
	v_mfma_f32_32x32x16_bf16 v[82:97], v[192:195], v[180:183], v[82:97]
	v_mfma_f32_32x32x16_bf16 v[66:81], v[192:195], v[184:187], v[66:81]
	v_mfma_f32_32x32x16_bf16 v[50:65], v[196:199], v[180:183], v[50:65]
	v_mfma_f32_32x32x16_bf16 v[34:49], v[196:199], v[184:187], v[34:49]
	v_mfma_f32_32x32x16_bf16 v[16:31], v[204:207], v[180:183], v[16:31]
	v_mfma_f32_32x32x16_bf16 v[0:15], v[204:207], v[184:187], v[0:15]
	s_cbranch_scc0 .LBB0_213
	v_add_u32_e32 v32, 1, v140
	v_cmp_ne_u32_e32 vcc, 2, v140
	v_lshlrev_b32_e32 v149, 1, v164
	v_lshlrev_b32_e32 v151, 1, v163
	v_cndmask_b32_e32 v32, 0, v32, vcc
	v_mul_lo_u32 v141, v32, s95
	v_lshlrev_b32_e32 v148, 1, v141
	v_add_u32_e32 v150, v148, v149
	v_lshl_add_u64 v[142:143], s[12:13], 0, v[138:139]
	v_lshlrev_b64 v[130:131], 1, v[130:131]
	v_readfirstlane_b32 s12, v150
	v_add_u32_e32 v162, v148, v151
	v_lshl_add_u64 v[144:145], v[142:143], 0, v[130:131]
	s_mov_b32 m0, s12
	v_lshlrev_b64 v[132:133], 1, v[132:133]
	v_readfirstlane_b32 s12, v162
	v_add_u32_e32 v163, v148, v166
	global_load_lds_dwordx4 v[144:145], off
	v_lshl_add_u64 v[146:147], v[142:143], 0, v[132:133]
	s_mov_b32 m0, s12
	v_lshl_add_u64 v[134:135], v[134:135], 1, v[142:143]
	v_readfirstlane_b32 s12, v163
	v_lshl_add_u64 v[136:137], v[136:137], 1, v[142:143]
	v_add_u32_e32 v142, v148, v165
	global_load_lds_dwordx4 v[146:147], off
	s_mov_b32 m0, s12
	v_readfirstlane_b32 s12, v142
	v_lshl_add_u64 v[138:139], s[14:15], 0, v[138:139]
	v_add_u32_e32 v142, 0x4000, v150
	global_load_lds_dwordx4 v[134:135], off
	s_mov_b32 m0, s12
	v_lshl_add_u64 v[130:131], v[138:139], 0, v[130:131]
	v_readfirstlane_b32 s12, v142
	v_lshl_add_u64 v[132:133], v[138:139], 0, v[132:133]
	v_add_u32_e32 v138, 0x4000, v162
	global_load_lds_dwordx4 v[136:137], off
	s_mov_b32 m0, s12
	v_readfirstlane_b32 s12, v138
	v_add_u32_e32 v138, 0x3000, v141
	v_cmp_ne_u32_e32 vcc, 2, v32
	global_load_lds_dwordx4 v[130:131], off
	s_nop 0
	v_cndmask_b32_e32 v32, 0, v138, vcc
	v_lshlrev_b32_e32 v32, 1, v32
	v_add_u32_e32 v141, v32, v149
	s_mov_b32 m0, s12
	v_readfirstlane_b32 s12, v141
	v_add_u32_e32 v142, v32, v151
	global_load_lds_dwordx4 v[132:133], off
	v_lshl_add_u64 v[138:139], v[144:145], 0, 64
	s_mov_b32 m0, s12
	v_readfirstlane_b32 s12, v142
	global_load_lds_dwordx4 v[138:139], off
	v_lshl_add_u64 v[138:139], v[146:147], 0, 64
	s_mov_b32 m0, s12
	v_lshl_add_u64 v[134:135], v[134:135], 0, 64
	global_load_lds_dwordx4 v[138:139], off
	v_add_u32_e32 v138, v32, v166
	v_add_u32_e32 v32, v32, v165
	v_readfirstlane_b32 s12, v138
	s_mov_b32 m0, s12
	v_readfirstlane_b32 s12, v32
	v_add_u32_e32 v32, 0x4000, v141
	global_load_lds_dwordx4 v[134:135], off
	v_lshl_add_u64 v[134:135], v[136:137], 0, 64
	s_mov_b32 m0, s12
	v_readfirstlane_b32 s12, v32
	v_add_u32_e32 v32, 0x4000, v142
	global_load_lds_dwordx4 v[134:135], off
	v_lshl_add_u64 v[130:131], v[130:131], 0, 64
	s_mov_b32 m0, s12
	v_readfirstlane_b32 s12, v32
	global_load_lds_dwordx4 v[130:131], off
	v_lshl_add_u64 v[130:131], v[132:133], 0, 64
	s_mov_b32 m0, s12
	s_nop 0
	global_load_lds_dwordx4 v[130:131], off

; template <bool VT>
; DI int gemm_kloop(const bf16_t* Ag, size_t lda, const bf16_t* Bg, size_t ldb, int nk, bf16_t* ring, f32x16 (&acc)[4][2], int tid, int wm, int wn,
;                   int r, int h, int st0, bool pre, const bf16_t* AgN, const bf16_t* BgN) {
;   const int wid = tid >> 6, lane = tid & 63;
;   const unsigned base = (unsigned)(unsigned long long)ring;
;   const int q = (r >> 2) & 3;
;   const unsigned rA = base + (unsigned)(wm * 128 + r) * 64u, rB = base + (unsigned)STG_A * 2u + (unsigned)(wn * 64 + r) * 64u;
;   const unsigned oA0 = rA + (unsigned)((h ^ q) & 3) * 16u, oA1 = rA + (unsigned)(((2 + h) ^ q) & 3) * 16u;
;   const unsigned oB0 = rB + (unsigned)((h ^ q) & 3) * 16u, oB1 = rB + (unsigned)(((2 + h) ^ q) & 3) * 16u;
;   int st = st0;
;   if (!pre) {
;     dma_issue(Ag, lda, Bg, ldb, 0, ring + st * STG, wid, lane);
;     dma_issue(Ag, lda, Bg, ldb, 1, ring + (st == 2 ? 0 : st + 1) * STG, wid, lane);
;   }
;     ...
;   f32x16 acc[4][2];
; #pragma unroll
;   for (int a = 0; a < 4; ++a)
; #pragma unroll
;     for (int b = 0; b < 2; ++b)
; #pragma unroll
;       for (int i = 0; i < 16; ++i) acc[a][b][i] = 0.f;
.LBB0_512:
	s_ashr_i32 s9, s18, 31
	s_ashr_i32 s8, s18, 3
	s_lshr_b32 s9, s9, 26
	s_add_i32 s9, s8, s9
	s_ashr_i32 s27, s9, 6
	s_andn2_b32 s9, s9, 63
	s_sub_i32 s8, s8, s9
	s_and_b32 s9, s18, 7
	s_add_i32 s9, s27, s9
	v_mov_b32_e32 v143, v242
	s_lshl_b32 s20, s8, 8
	s_lshl_b32 s8, s8, 4
	s_lshl_b32 s9, s9, 11
	v_ashrrev_i32_e32 v145, 6, v143
	s_and_b32 s28, s20, 0x700
	s_and_b32 s21, s8, 0xffffff80
	v_bfe_u32 v144, v143, 5, 1
	s_or_b32 s20, s9, s28
	s_mul_i32 s8, s21, 0x440
	s_waitcnt vmcnt(0)
	v_and_b32_e32 v146, 31, v143
	v_and_b32_e32 v151, 1, v145
	v_lshrrev_b32_e32 v0, 2, v143
	s_and_b32 s26, s17, 7
	s_ashr_i32 s9, s8, 31
	s_mul_i32 s22, s20, 0x880
	v_lshlrev_b32_e32 v2, 6, v143
	v_lshlrev_b32_e32 v3, 6, v146
	v_lshlrev_b32_e32 v4, 12, v151
	v_bitop3_b32 v0, v0, v144, 3 bitop3:0x6c
	s_mul_hi_i32 s23, s20, 0x880
	s_add_u32 s22, s10, s22
	v_bfe_u32 v1, v143, 2, 2
	v_and_or_b32 v2, v2, s93, v3
	v_or3_b32 v3, v3, v4, s94
	v_lshlrev_b32_e32 v0, 4, v0
	v_bfe_u32 v142, v143, 4, 2
	s_addc_u32 s23, s11, s23
	s_lshl_b64 s[8:9], s[8:9], 1
	v_or_b32_e32 v147, v0, v2
	v_bitop3_b32 v1, v144, v1, 2 bitop3:0x36
	v_or_b32_e32 v149, v3, v0
	v_bitop3_b32 v0, v142, v143, 3 bitop3:0x78
	s_add_u32 s24, s12, s8
	v_lshlrev_b32_e32 v1, 4, v1
	s_mul_i32 s29, s19, 0x3000
	v_bfe_u32 v8, v143, 2, 4
	v_lshlrev_b32_e32 v32, 4, v0
	s_addc_u32 s25, s13, s9
	v_or_b32_e32 v148, v1, v2
	v_or_b32_e32 v150, v1, v3
	s_lshl_b32 s33, s29, 1
	v_lshl_add_u64 v[0:1], s[22:23], 0, v[32:33]
	v_lshl_or_b32 v12, v145, 4, v8
	v_lshlrev_b32_e32 v13, 10, v145
	v_mad_i64_i32 v[2:3], s[22:23], v12, s74, v[0:1]
	v_add_u32_e32 v14, s33, v13
	v_add_u32_e32 v6, 4, v145
	v_readfirstlane_b32 s22, v14
	v_lshl_or_b32 v15, v6, 4, v8
	v_lshlrev_b32_e32 v16, 10, v6
	s_mov_b32 m0, s22
	v_mad_i64_i32 v[4:5], s[22:23], v15, s74, v[0:1]
	v_add_u32_e32 v17, s33, v16
	v_add_u32_e32 v9, 8, v145
	v_lshlrev_b32_e32 v153, 9, v6
	v_readfirstlane_b32 s22, v17
	v_lshl_or_b32 v6, v9, 4, v8
	v_lshlrev_b32_e32 v154, 10, v9
	s_waitcnt lgkmcnt(0)
	s_barrier
	global_load_lds_dwordx4 v[2:3], off
	s_mov_b32 m0, s22
	v_mad_i64_i32 v[6:7], s[22:23], v6, s74, v[0:1]
	v_add_u32_e32 v9, s33, v154
	global_load_lds_dwordx4 v[4:5], off
	v_readfirstlane_b32 s22, v9
	v_add_u32_e32 v9, 12, v145
	v_lshl_or_b32 v8, v9, 4, v8
	v_lshlrev_b32_e32 v155, 10, v9
	s_mov_b32 m0, s22
	v_mad_i64_i32 v[0:1], s[22:23], v8, s74, v[0:1]
	v_add_u32_e32 v8, s33, v155
	global_load_lds_dwordx4 v[6:7], off
	v_readfirstlane_b32 s22, v8
	v_lshl_add_u64 v[8:9], s[24:25], 0, v[32:33]
	s_mov_b32 m0, s22
	v_mad_i64_i32 v[10:11], s[22:23], v12, s74, v[8:9]
	v_add_u32_e32 v14, 0x4000, v14
	global_load_lds_dwordx4 v[0:1], off
	v_readfirstlane_b32 s22, v14
	s_mov_b32 m0, s22
	v_mad_i64_i32 v[8:9], s[22:23], v15, s74, v[8:9]
	v_add_u32_e32 v14, 0x4000, v17
	s_addk_i32 s29, 0x3000
	v_readfirstlane_b32 s22, v14
	s_cmp_lg_u32 s19, 2
	global_load_lds_dwordx4 v[10:11], off
	s_mov_b32 m0, s22
	s_cselect_b32 s22, s29, 0
	s_lshl_b32 s22, s22, 1
	v_add_u32_e32 v13, s22, v13
	global_load_lds_dwordx4 v[8:9], off
	v_readfirstlane_b32 s23, v13
	v_lshl_add_u64 v[2:3], v[2:3], 0, 64
	s_mov_b32 m0, s23
	v_lshl_add_u64 v[0:1], v[0:1], 0, 64
	global_load_lds_dwordx4 v[2:3], off
	v_lshl_add_u64 v[2:3], v[4:5], 0, 64
	v_add_u32_e32 v4, s22, v16
	v_add_u32_e32 v5, s22, v154
	v_readfirstlane_b32 s23, v4
	s_mov_b32 m0, s23
	v_readfirstlane_b32 s23, v5
	global_load_lds_dwordx4 v[2:3], off
	v_lshl_add_u64 v[2:3], v[6:7], 0, 64
	s_mov_b32 m0, s23
	s_add_u32 s8, s15, s8
	global_load_lds_dwordx4 v[2:3], off
	v_add_u32_e32 v2, s22, v155
	s_addc_u32 s9, s16, s9
	v_readfirstlane_b32 s22, v2
	v_add_u32_e32 v2, 0x4000, v13
	s_mov_b32 m0, s22
	v_readfirstlane_b32 s22, v2
	v_add_u32_e32 v2, 0x4000, v4
	global_load_lds_dwordx4 v[0:1], off
	v_lshl_add_u64 v[0:1], v[10:11], 0, 64
	s_mov_b32 m0, s22
	v_readfirstlane_b32 s22, v2
	global_load_lds_dwordx4 v[0:1], off
	v_lshl_add_u64 v[0:1], v[8:9], 0, 64
	s_mov_b32 m0, s22
	v_mad_i64_i32 v[2:3], s[22:23], v12, s74, 0
	global_load_lds_dwordx4 v[0:1], off
	v_add_u32_e32 v0, 64, v12
	v_mad_i64_i32 v[0:1], s[22:23], v0, s74, 0
	v_or_b32_e32 v0, v0, v32
	v_or_b32_e32 v2, v2, v32
	s_add_i32 s27, s27, s26
	v_lshl_add_u64 v[130:131], s[8:9], 0, v[0:1]
	v_lshl_add_u64 v[132:133], s[8:9], 0, v[2:3]
	s_lshl_b32 s8, s27, 11
	s_or_b32 s22, s8, s28
	s_mul_hi_i32 s9, s22, 0x880
	s_mul_i32 s8, s22, 0x880
	v_add_u32_e32 v6, 0xc0, v12
	v_mov_b64_e32 v[4:5], s[8:9]
	v_mad_i64_i32 v[6:7], s[8:9], v6, s74, v[4:5]
	v_or_b32_e32 v6, v6, v32
	v_lshl_add_u64 v[134:135], s[6:7], 0, v[6:7]
	v_add_u32_e32 v6, 0x80, v12
	v_mad_i64_i32 v[0:1], s[8:9], s22, v211, v[0:1]
	v_mad_i64_i32 v[4:5], s[8:9], v6, s74, v[4:5]
	v_lshl_add_u64 v[138:139], s[6:7], 0, v[0:1]
	v_mad_i64_i32 v[0:1], s[8:9], s22, v211, v[2:3]
	v_or_b32_e32 v4, v4, v32
	v_lshl_add_u64 v[140:141], s[6:7], 0, v[0:1]
	v_mov_b32_e32 v0, 0
	v_lshlrev_b32_e32 v152, 9, v145
	v_lshl_add_u64 v[136:137], s[6:7], 0, v[4:5]
	s_mov_b64 s[8:9], 0
	v_mov_b32_e32 v1, v0
	v_mov_b32_e32 v2, v0
	v_mov_b32_e32 v3, v0
	v_mov_b32_e32 v4, v0
	v_mov_b32_e32 v5, v0
	v_mov_b32_e32 v6, v0
	v_mov_b32_e32 v7, v0
	v_mov_b32_e32 v8, v0
	v_mov_b32_e32 v9, v0
	v_mov_b32_e32 v10, v0
	v_mov_b32_e32 v11, v0
	v_mov_b32_e32 v12, v0
	v_mov_b32_e32 v13, v0
	v_mov_b32_e32 v14, v0
	v_mov_b32_e32 v15, v0
	v_mov_b32_e32 v16, v0
	v_mov_b32_e32 v17, v0
	v_mov_b32_e32 v18, v0
	v_mov_b32_e32 v19, v0
	v_mov_b32_e32 v20, v0
	v_mov_b32_e32 v21, v0
	v_mov_b32_e32 v22, v0
	v_mov_b32_e32 v23, v0
	v_mov_b32_e32 v24, v0
	v_mov_b32_e32 v25, v0
	v_mov_b32_e32 v26, v0
	v_mov_b32_e32 v27, v0
	v_mov_b32_e32 v28, v0
	v_mov_b32_e32 v29, v0
	v_mov_b32_e32 v30, v0
; #define MFMA(a, b, c) __builtin_amdgcn_mfma_f32_32x32x16_bf16((a), (b), (c), 0, 0, 0)
; #define DSR(dst, addr, off) asm volatile("ds_read_b128 %0, %1 offset:" #off : "=&v"(dst) : "v"(addr))
; DI void dma_issue(const bf16_t* Ag, size_t lda, const bf16_t* Bg, size_t ldb, int kt, bf16_t* stage, int wid, int lane) {
;   const int rl = lane >> 2, c = (lane & 3) ^ ((lane >> 4) & 3);
; #pragma unroll
;   for (int i = 0; i < 4; ++i) {
;     const int j = wid + 4 * i;
;     __builtin_amdgcn_global_load_lds((const unsigned*)(Ag + (size_t)(16 * j + rl) * lda + kt * 32 + c * 8), (unsigned*)(stage + j * 512), 16, 0, 0);
;   }
; #pragma unroll
;   for (int i = 0; i < 2; ++i) {
;     const int j = wid + 4 * i;
;     __builtin_amdgcn_global_load_lds((const unsigned*)(Bg + (size_t)(16 * j + rl) * ldb + kt * 32 + c * 8), (unsigned*)(stage + STG_A + j * 512), 16, 0, 0);
;   }
; }
; template <bool VT>
; DI void g_compute_asm(unsigned aA0, unsigned aA1, unsigned aB0, unsigned aB1, f32x16 (&acc)[4][2]) {
;   bf16x8 a0[4], a1[4], b0[2], b1[2];
;   DSR(b0[0], aB0, 0); DSR(b0[1], aB0, 2048);
;   DSR(a0[0], aA0, 0); DSR(a0[1], aA0, 2048); DSR(a0[2], aA0, 4096); DSR(a0[3], aA0, 6144);
;   DSR(b1[0], aB1, 0); DSR(b1[1], aB1, 2048);
;   DSR(a1[0], aA1, 0); DSR(a1[1], aA1, 2048); DSR(a1[2], aA1, 4096); DSR(a1[3], aA1, 6144);
;   asm volatile("s_waitcnt lgkmcnt(6)" : "+v"(b0[0]), "+v"(b0[1]), "+v"(a0[0]), "+v"(a0[1]), "+v"(a0[2]), "+v"(a0[3]));
; #pragma unroll
;   for (int mi = 0; mi < 4; ++mi)
; #pragma unroll
;     for (int ni = 0; ni < 2; ++ni) {
;       if (VT) acc[mi][ni] = MFMA(a0[mi], b0[ni], acc[mi][ni]);
;       else acc[mi][ni] = MFMA(b0[ni], a0[mi], acc[mi][ni]);
;     }
;   __builtin_amdgcn_sched_barrier(0);
;   asm volatile("s_waitcnt lgkmcnt(0)" : "+v"(b1[0]), "+v"(b1[1]), "+v"(a1[0]), "+v"(a1[1]), "+v"(a1[2]), "+v"(a1[3]));
; #pragma unroll
;   for (int mi = 0; mi < 4; ++mi)
; #pragma unroll
;     for (int ni = 0; ni < 2; ++ni) {
;       if (VT) acc[mi][ni] = MFMA(a1[mi], b1[ni], acc[mi][ni]);
;       else acc[mi][ni] = MFMA(b1[ni], a1[mi], acc[mi][ni]);
;     }
; }
	v_mov_b32_e32 v31, v0
	v_mov_b32_e32 v34, v0
	v_mov_b32_e32 v35, v0
	v_mov_b32_e32 v36, v0
	v_mov_b32_e32 v37, v0
	v_mov_b32_e32 v38, v0
	v_mov_b32_e32 v39, v0
	v_mov_b32_e32 v40, v0
	v_mov_b32_e32 v41, v0
	v_mov_b32_e32 v42, v0
	v_mov_b32_e32 v43, v0
	v_mov_b32_e32 v44, v0
	v_mov_b32_e32 v45, v0
	v_mov_b32_e32 v46, v0
	v_mov_b32_e32 v47, v0
	v_mov_b32_e32 v48, v0
	v_mov_b32_e32 v49, v0
	v_mov_b32_e32 v50, v0
	v_mov_b32_e32 v51, v0
	v_mov_b32_e32 v52, v0
	v_mov_b32_e32 v53, v0
	v_mov_b32_e32 v54, v0
	v_mov_b32_e32 v55, v0
	v_mov_b32_e32 v56, v0
	v_mov_b32_e32 v57, v0
	v_mov_b32_e32 v58, v0
	v_mov_b32_e32 v59, v0
	v_mov_b32_e32 v60, v0
	v_mov_b32_e32 v61, v0
	v_mov_b32_e32 v62, v0
	v_mov_b32_e32 v63, v0
	v_mov_b32_e32 v64, v0
	v_mov_b32_e32 v65, v0
	v_mov_b32_e32 v66, v0
	v_mov_b32_e32 v67, v0
	v_mov_b32_e32 v68, v0
	v_mov_b32_e32 v69, v0
	v_mov_b32_e32 v70, v0
	v_mov_b32_e32 v71, v0
	v_mov_b32_e32 v72, v0
	v_mov_b32_e32 v73, v0
	v_mov_b32_e32 v74, v0
	v_mov_b32_e32 v75, v0
	v_mov_b32_e32 v76, v0
	v_mov_b32_e32 v77, v0
	v_mov_b32_e32 v78, v0
	v_mov_b32_e32 v79, v0
	v_mov_b32_e32 v80, v0
	v_mov_b32_e32 v81, v0
	v_mov_b32_e32 v82, v0
	v_mov_b32_e32 v83, v0
	v_mov_b32_e32 v84, v0
	v_mov_b32_e32 v85, v0
	v_mov_b32_e32 v86, v0
	v_mov_b32_e32 v87, v0
	v_mov_b32_e32 v88, v0
	v_mov_b32_e32 v89, v0
	v_mov_b32_e32 v90, v0
	v_mov_b32_e32 v91, v0
	v_mov_b32_e32 v92, v0
	v_mov_b32_e32 v93, v0
	v_mov_b32_e32 v94, v0
	v_mov_b32_e32 v95, v0
	v_mov_b32_e32 v96, v0
	v_mov_b32_e32 v97, v0
	s_waitcnt vmcnt(0)
	v_mov_b32_e32 v98, v0
	v_mov_b32_e32 v99, v0
	v_mov_b32_e32 v100, v0
	v_mov_b32_e32 v101, v0
	v_mov_b32_e32 v102, v0
	v_mov_b32_e32 v103, v0
	v_mov_b32_e32 v104, v0
	v_mov_b32_e32 v105, v0
	v_mov_b32_e32 v106, v0
	v_mov_b32_e32 v107, v0
	v_mov_b32_e32 v108, v0
	v_mov_b32_e32 v109, v0
	v_mov_b32_e32 v110, v0
	v_mov_b32_e32 v111, v0
	v_mov_b32_e32 v112, v0
	v_mov_b32_e32 v113, v0
	v_mov_b32_e32 v114, v0
	v_mov_b32_e32 v115, v0
	v_mov_b32_e32 v116, v0
	v_mov_b32_e32 v117, v0
	v_mov_b32_e32 v118, v0
	v_mov_b32_e32 v119, v0
	v_mov_b32_e32 v120, v0
	v_mov_b32_e32 v121, v0
	v_mov_b32_e32 v122, v0
	v_mov_b32_e32 v123, v0
	v_mov_b32_e32 v124, v0
	v_mov_b32_e32 v125, v0
	v_mov_b32_e32 v126, v0
	v_mov_b32_e32 v127, v0
	v_mov_b32_e32 v128, v0
	v_mov_b32_e32 v129, v0
	v_readfirstlane_b32 s99, v152
	s_lshl_b32 s99, s99, 1
.LBB0_513:
	s_mul_i32 s22, s19, 0x3000
	v_lshl_add_u64 v[156:157], v[140:141], 0, s[8:9]
	s_mul_i32 s98, s19, 0x3000
	s_addk_i32 s98, 0xd000
	s_cmp_lg_u32 s19, 0
	s_cselect_b32 s98, s98, 0x6000
	s_lshl_b32 s98, s98, 1
	s_add_u32 s98, s98, s99
	s_mul_i32 s22, s19, 0x6000
	v_add_u32_e32 v164, s22, v149
	v_add_u32_e32 v32, s22, v147
	v_add_u32_e32 v188, s22, v150
	v_add_u32_e32 v204, s22, v148
	s_mov_b32 m0, s98
	s_waitcnt vmcnt(6)
	s_barrier
	global_load_lds_dwordx4 v[156:157], off
	ds_read_b128 v[156:159], v164 offset:0
	ds_read_b128 v[160:163], v164 offset:2048
	ds_read_b128 v[164:167], v32 offset:0
	ds_read_b128 v[168:171], v32 offset:2048
	ds_read_b128 v[172:175], v32 offset:4096
	ds_read_b128 v[176:179], v32 offset:6144
	ds_read_b128 v[180:183], v188 offset:0
	ds_read_b128 v[184:187], v188 offset:2048
	ds_read_b128 v[188:191], v204 offset:0
	ds_read_b128 v[192:195], v204 offset:2048
	ds_read_b128 v[196:199], v204 offset:4096
	ds_read_b128 v[200:203], v204 offset:6144
	s_waitcnt lgkmcnt(9)
	v_mfma_f32_32x32x16_bf16 v[114:129], v[156:159], v[164:167], v[114:129]
	v_mfma_f32_32x32x16_bf16 v[98:113], v[160:163], v[164:167], v[98:113]
	s_add_u32 m0, s98, 0x1000
	v_lshl_add_u64 v[206:207], v[138:139], 0, s[8:9]
	global_load_lds_dwordx4 v[206:207], off
	s_waitcnt lgkmcnt(8)
	v_mfma_f32_32x32x16_bf16 v[82:97], v[156:159], v[168:171], v[82:97]
	v_mfma_f32_32x32x16_bf16 v[66:81], v[160:163], v[168:171], v[66:81]
	s_add_u32 m0, s98, 0x2000
	v_lshl_add_u64 v[206:207], v[136:137], 0, s[8:9]
	global_load_lds_dwordx4 v[206:207], off
	s_waitcnt lgkmcnt(7)
	v_mfma_f32_32x32x16_bf16 v[50:65], v[156:159], v[172:175], v[50:65]
	v_mfma_f32_32x32x16_bf16 v[34:49], v[160:163], v[172:175], v[34:49]
	s_add_u32 m0, s98, 0x3000
	v_lshl_add_u64 v[206:207], v[134:135], 0, s[8:9]
	global_load_lds_dwordx4 v[206:207], off
	s_waitcnt lgkmcnt(6)
	v_mfma_f32_32x32x16_bf16 v[16:31], v[156:159], v[176:179], v[16:31]
	v_mfma_f32_32x32x16_bf16 v[0:15], v[160:163], v[176:179], v[0:15]
	s_add_u32 m0, s98, 0x4000
	v_lshl_add_u64 v[206:207], v[132:133], 0, s[8:9]
	global_load_lds_dwordx4 v[206:207], off
	s_waitcnt lgkmcnt(3)
	v_mfma_f32_32x32x16_bf16 v[114:129], v[180:183], v[188:191], v[114:129]
	v_mfma_f32_32x32x16_bf16 v[98:113], v[184:187], v[188:191], v[98:113]
	s_add_u32 m0, s98, 0x5000
	v_lshl_add_u64 v[206:207], v[130:131], 0, s[8:9]
	global_load_lds_dwordx4 v[206:207], off
	s_add_i32 s22, s19, 1
	s_cmp_lg_u32 s19, 2
	s_cselect_b32 s19, s22, 0
	s_add_u32 s8, s8, 64
	s_addc_u32 s9, s9, 0
	s_cmpk_eq_i32 s8, 0x780
	s_waitcnt lgkmcnt(2)
	v_mfma_f32_32x32x16_bf16 v[82:97], v[180:183], v[192:195], v[82:97]
	v_mfma_f32_32x32x16_bf16 v[66:81], v[184:187], v[192:195], v[66:81]
	s_waitcnt lgkmcnt(1)
	v_mfma_f32_32x32x16_bf16 v[50:65], v[180:183], v[196:199], v[50:65]
	v_mfma_f32_32x32x16_bf16 v[34:49], v[184:187], v[196:199], v[34:49]
	s_waitcnt lgkmcnt(0)
	v_mfma_f32_32x32x16_bf16 v[16:31], v[180:183], v[200:203], v[16:31]
	v_mfma_f32_32x32x16_bf16 v[0:15], v[184:187], v[200:203], v[0:15]
	s_cbranch_scc0 .LBB0_513
	s_mul_i32 s8, s19, 0x6000
	s_waitcnt vmcnt(6)
	s_barrier
; DI u32x2 pack4(float a, float b, float c, float d) { u32x2 w; w.x = pack2(a, b); w.y = pack2(c, d); return w; }
; template <bool VT>
; DI int gemm_kloop(const bf16_t* Ag, size_t lda, const bf16_t* Bg, size_t ldb, int nk, bf16_t* ring, f32x16 (&acc)[4][2], int tid, int wm, int wn,
;                   int r, int h, int st0, bool pre, const bf16_t* AgN, const bf16_t* BgN) {
;     ...
;   asm volatile("s_waitcnt vmcnt(0)" ::: "memory");
;   __builtin_amdgcn_s_barrier();
;   if (AgN) {
;     const int s1 = st == 2 ? 0 : st + 1, s2 = s1 == 2 ? 0 : s1 + 1;
;     dma_issue(AgN, lda, BgN, ldb, 0, ring + s1 * STG, wid, lane);
;     dma_issue(AgN, lda, BgN, ldb, 1, ring + s2 * STG, wid, lane);
;   }
;   {
;     const unsigned so = (unsigned)st * (unsigned)(STG * 2);
;     g_compute_asm<VT>(oA0 + so, oA1 + so, oB0 + so, oB1 + so, acc);
;   }
;   asm volatile("s_waitcnt lgkmcnt(0)" ::: "memory");
;   return st;
;   DI void operator()(const f32x16 (&acc)[4][2], bool vt, int row0, int col0, int r, int h, const float* sR, float* stage) const {
;     const int lane = h * 32 + r, lr = lane >> 4, lc = (lane & 15) * 4;
; #pragma unroll
;     for (int mi = 0; mi < 4; ++mi) {
; #pragma unroll
;       for (int ni = 0; ni < 2; ++ni)
; #pragma unroll
;         for (int g = 0; g < 4; ++g)
;           *(f32x4*)(stage + r * 68 + ni * 32 + 8 * g + 4 * h) = (f32x4){acc[mi][ni][4 * g], acc[mi][ni][4 * g + 1], acc[mi][ni][4 * g + 2], acc[mi][ni][4 * g + 3]};
; #pragma unroll
;       for (int j = 0; j < 8; ++j) {
;         const int rr = j * 4 + lr;
;         f32x4 v = *(const f32x4*)(stage + rr * 68 + lc);
;         const size_t row = row0 + mi * 32 + rr, idx = row * DM + col0 + lc;
;         const f32x4 xin = *(const f32x4*)(rin + idx);
;         v += xin;
;         *(f32x4*)(out + idx) = v;
;         *(u32x2*)(xb + row * LDX + col0 + lc) = pack4(v.x, v.y, v.z, v.w);
;         float ss = (v.x * v.x + v.y * v.y) + (v.z * v.z + v.w * v.w);
;         ss += __shfl_xor(ss, 1); ss += __shfl_xor(ss, 2); ss += __shfl_xor(ss, 4); ss += __shfl_xor(ss, 8);
;         if ((lane & 15) == 0) ssq[row * 16 + (col0 >> 6)] = ss;
;       }
	v_add_u32_e32 v32, s8, v147
	v_add_u32_e32 v140, s8, v149
	ds_read_b128 v[132:135], v140 offset:0
	ds_read_b128 v[136:139], v140 offset:2048
	ds_read_b128 v[152:155], v32 offset:0
	ds_read_b128 v[156:159], v32 offset:2048
	ds_read_b128 v[160:163], v32 offset:4096
	ds_read_b128 v[164:167], v32 offset:6144
	v_add_u32_e32 v131, s8, v148
	v_add_u32_e32 v141, s8, v150
	ds_read_b128 v[168:171], v141 offset:0
	ds_read_b128 v[172:175], v141 offset:2048
	ds_read_b128 v[176:179], v131 offset:0
	ds_read_b128 v[180:183], v131 offset:2048
	ds_read_b128 v[184:187], v131 offset:4096
	ds_read_b128 v[188:191], v131 offset:6144
	s_waitcnt lgkmcnt(6)
	v_lshl_or_b32 v130, v151, 6, s21
	v_mfma_f32_32x32x16_bf16 v[98:113], v[136:139], v[152:155], v[98:113]
	v_mfma_f32_32x32x16_bf16 v[82:97], v[132:135], v[156:159], v[82:97]
	v_mfma_f32_32x32x16_bf16 v[66:81], v[136:139], v[156:159], v[66:81]
	v_mfma_f32_32x32x16_bf16 v[50:65], v[132:135], v[160:163], v[50:65]
	v_mfma_f32_32x32x16_bf16 v[34:49], v[136:139], v[160:163], v[34:49]
	v_mfma_f32_32x32x16_bf16 v[16:31], v[132:135], v[164:167], v[16:31]
	v_mfma_f32_32x32x16_bf16 v[0:15], v[136:139], v[164:167], v[0:15]
	v_mfma_f32_32x32x16_bf16 v[114:129], v[132:135], v[152:155], v[114:129]
	s_waitcnt lgkmcnt(0)
	s_add_i32 s8, s19, 1
	v_mfma_f32_32x32x16_bf16 v[98:113], v[172:175], v[176:179], v[98:113]
	s_cmp_lg_u32 s19, 2
	s_cselect_b32 s19, s8, 0
	s_mul_i32 s8, s19, 0x6000
	s_waitcnt vmcnt(0)
	s_barrier
	v_add_u32_e32 v32, s8, v147
	v_add_u32_e32 v131, s8, v148
	v_mfma_f32_32x32x16_bf16 v[82:97], v[168:171], v[180:183], v[82:97]
	v_add_u32_e32 v140, s8, v149
	v_add_u32_e32 v141, s8, v150
	ds_read_b128 v[132:135], v140 offset:0
	ds_read_b128 v[136:139], v140 offset:2048
	ds_read_b128 v[148:151], v32 offset:0
	ds_read_b128 v[152:155], v32 offset:2048
	ds_read_b128 v[156:159], v32 offset:4096
	v_mfma_f32_32x32x16_bf16 v[66:81], v[172:175], v[180:183], v[66:81]
	ds_read_b128 v[160:163], v32 offset:6144
	ds_read_b128 v[164:167], v141 offset:0
	v_mfma_f32_32x32x16_bf16 v[50:65], v[168:171], v[184:187], v[50:65]
	v_mfma_f32_32x32x16_bf16 v[34:49], v[172:175], v[184:187], v[34:49]
	v_mfma_f32_32x32x16_bf16 v[16:31], v[168:171], v[188:191], v[16:31]
	v_mfma_f32_32x32x16_bf16 v[0:15], v[172:175], v[188:191], v[0:15]
	v_mfma_f32_32x32x16_bf16 v[114:129], v[168:171], v[176:179], v[114:129]
	ds_read_b128 v[168:171], v141 offset:2048
	ds_read_b128 v[172:175], v131 offset:0
	ds_read_b128 v[176:179], v131 offset:2048
	ds_read_b128 v[180:183], v131 offset:4096
	ds_read_b128 v[184:187], v131 offset:6144
	s_waitcnt lgkmcnt(6)
	s_nop 0
	v_mfma_f32_32x32x16_bf16 v[98:113], v[136:139], v[148:151], v[98:113]
	v_mfma_f32_32x32x16_bf16 v[82:97], v[132:135], v[152:155], v[82:97]
	v_mfma_f32_32x32x16_bf16 v[66:81], v[136:139], v[152:155], v[66:81]
	v_mfma_f32_32x32x16_bf16 v[50:65], v[132:135], v[156:159], v[50:65]
	v_mfma_f32_32x32x16_bf16 v[34:49], v[136:139], v[156:159], v[34:49]
	v_mfma_f32_32x32x16_bf16 v[16:31], v[132:135], v[160:163], v[16:31]
	v_mfma_f32_32x32x16_bf16 v[0:15], v[136:139], v[160:163], v[0:15]
	v_mfma_f32_32x32x16_bf16 v[114:129], v[132:135], v[148:151], v[114:129]
	s_waitcnt lgkmcnt(0)
	v_mul_lo_u32 v135, v145, s68
	v_mfma_f32_32x32x16_bf16 v[114:129], v[164:167], v[172:175], v[114:129]
	v_and_b32_e32 v32, 0xffffff80, v143
	v_add_u32_e32 v132, s20, v32
	v_mad_u32_u24 v32, v146, s69, v135
	v_lshlrev_b32_e32 v131, 4, v144
	v_add_u32_e32 v133, v32, v131
	s_waitcnt lgkmcnt(0)
	s_waitcnt vmcnt(0) lgkmcnt(0)
	v_mfma_f32_32x32x16_bf16 v[98:113], v[168:171], v[172:175], v[98:113]
	s_barrier
	v_and_b32_e32 v134, 15, v143
	v_ashrrev_i32_e32 v131, 31, v130
	s_nop 1
	ds_write_b128 v133, v[114:117]
	ds_write_b128 v133, v[118:121] offset:32
	ds_write_b128 v133, v[122:125] offset:64
	ds_write_b128 v133, v[126:129] offset:96
	s_nop 2
	ds_write_b128 v133, v[98:101] offset:128
	ds_write_b128 v133, v[102:105] offset:160
	ds_write_b128 v133, v[106:109] offset:192
	v_or_b32_e32 v102, v132, v142
	v_lshlrev_b32_e32 v32, 4, v134
	v_ashrrev_i32_e32 v103, 31, v102
	v_lshl_add_u64 v[98:99], v[130:131], 2, s[0:1]
	v_lshl_add_u64 v[98:99], v[98:99], 0, v[32:33]
	v_lshlrev_b64 v[100:101], 12, v[102:103]
	ds_write_b128 v133, v[110:113] offset:224
	v_lshl_add_u64 v[118:119], v[98:99], 0, v[100:101]
	flat_load_dwordx4 v[110:113], v[118:119]
	v_and_b32_e32 v101, 64, v208
	v_xor_b32_e32 v100, 1, v208
	v_add_u32_e32 v101, 64, v101
	v_xor_b32_e32 v104, 2, v208
	v_cmp_lt_i32_e32 vcc, v100, v101
	v_or_b32_e32 v108, v135, v32
	v_xor_b32_e32 v105, 4, v208
	v_cndmask_b32_e32 v32, v208, v100, vcc
	v_cmp_lt_i32_e32 vcc, v104, v101
	v_lshlrev_b32_e32 v106, 2, v32
	v_xor_b32_e32 v107, 8, v208
	v_cndmask_b32_e32 v100, v208, v104, vcc
	v_mad_u32_u24 v104, v142, s69, v108
	ds_read_b128 v[114:117], v104
	v_cmp_lt_i32_e32 vcc, v105, v101
	v_mfma_f32_32x32x16_bf16 v[82:97], v[164:167], v[176:179], v[82:97]
	s_waitcnt vmcnt(0) lgkmcnt(0)
	v_add_f32_e64 v112, v116, v112
	v_add_f32_e64 v113, v117, v113
	v_add_f32_e64 v110, v114, v110
	v_add_f32_e64 v111, v115, v111
	v_cndmask_b32_e32 v104, v208, v105, vcc
	v_lshlrev_b32_e32 v105, 2, v100
	v_mul_f32_e32 v32, v111, v111
	v_mul_f32_e32 v100, v113, v113
	v_fmac_f32_e32 v32, v110, v110
	v_fmac_f32_e32 v100, v112, v112
	v_add_f32_e32 v32, v32, v100
	ds_bpermute_b32 v100, v106, v32
	v_lshlrev_b32_e32 v104, 2, v104
	v_mfma_f32_32x32x16_bf16 v[66:81], v[168:171], v[176:179], v[66:81]
	v_cmp_lt_i32_e32 vcc, v107, v101
	flat_store_dwordx4 v[118:119], v[110:113]
	s_waitcnt lgkmcnt(0)
	v_add_f32_e32 v32, v32, v100
	ds_bpermute_b32 v109, v105, v32
	v_cndmask_b32_e32 v101, v208, v107, vcc
	v_lshlrev_b32_e32 v107, 2, v101
	v_cvt_pk_bf16_f32 v114, v110, v111
	v_mfma_f32_32x32x16_bf16 v[50:65], v[164:167], v[180:183], v[50:65]
	s_waitcnt lgkmcnt(0)
	v_add_f32_e32 v32, v32, v109
	ds_bpermute_b32 v109, v104, v32
	v_mov_b64_e32 v[110:111], s[2:3]
	v_cvt_pk_bf16_f32 v115, v112, v113
	v_mad_i64_i32 v[112:113], s[8:9], v102, s74, v[110:111]
	s_waitcnt lgkmcnt(0)
	v_add_f32_e32 v109, v32, v109
	v_mfma_f32_32x32x16_bf16 v[34:49], v[168:171], v[180:183], v[34:49]
	ds_bpermute_b32 v110, v107, v109
	v_ashrrev_i32_e32 v100, 6, v130
	v_lshl_add_u64 v[112:113], v[130:131], 1, v[112:113]
	v_lshlrev_b32_e32 v32, 3, v134
	v_cmp_eq_u32_e32 vcc, 0, v134
	v_ashrrev_i32_e32 v101, 31, v100
	v_lshl_add_u64 v[112:113], v[112:113], 0, v[32:33]
	v_mfma_f32_32x32x16_bf16 v[16:31], v[164:167], v[184:187], v[16:31]
	flat_store_dwordx2 v[112:113], v[114:115]
	v_mfma_f32_32x32x16_bf16 v[0:15], v[168:171], v[184:187], v[0:15]
	s_and_saveexec_b64 s[8:9], vcc
	s_cbranch_execz .LBB0_516
	v_lshlrev_b64 v[102:103], 6, v[102:103]
	v_lshl_add_u64 v[102:103], s[4:5], 0, v[102:103]
	v_lshl_add_u64 v[102:103], v[100:101], 2, v[102:103]
	s_waitcnt lgkmcnt(0)
	v_add_f32_e32 v32, v109, v110
	flat_store_dword v[102:103], v32

; #define MFMA(a, b, c) __builtin_amdgcn_mfma_f32_32x32x16_bf16((a), (b), (c), 0, 0, 0)
; #define DSR(dst, addr, off) asm volatile("ds_read_b128 %0, %1 offset:" #off : "=&v"(dst) : "v"(addr))
; DI void dma_issue(const bf16_t* Ag, size_t lda, const bf16_t* Bg, size_t ldb, int kt, bf16_t* stage, int wid, int lane) {
;   const int rl = lane >> 2, c = (lane & 3) ^ ((lane >> 4) & 3);
; #pragma unroll
;   for (int i = 0; i < 4; ++i) {
;     const int j = wid + 4 * i;
;     __builtin_amdgcn_global_load_lds((const unsigned*)(Ag + (size_t)(16 * j + rl) * lda + kt * 32 + c * 8), (unsigned*)(stage + j * 512), 16, 0, 0);
;   }
; #pragma unroll
;   for (int i = 0; i < 2; ++i) {
;     const int j = wid + 4 * i;
;     __builtin_amdgcn_global_load_lds((const unsigned*)(Bg + (size_t)(16 * j + rl) * ldb + kt * 32 + c * 8), (unsigned*)(stage + STG_A + j * 512), 16, 0, 0);
;   }
; }
; template <bool VT>
; DI void g_compute_asm(unsigned aA0, unsigned aA1, unsigned aB0, unsigned aB1, f32x16 (&acc)[4][2]) {
;   bf16x8 a0[4], a1[4], b0[2], b1[2];
;   DSR(b0[0], aB0, 0); DSR(b0[1], aB0, 2048);
;   DSR(a0[0], aA0, 0); DSR(a0[1], aA0, 2048); DSR(a0[2], aA0, 4096); DSR(a0[3], aA0, 6144);
;   DSR(b1[0], aB1, 0); DSR(b1[1], aB1, 2048);
;   DSR(a1[0], aA1, 0); DSR(a1[1], aA1, 2048); DSR(a1[2], aA1, 4096); DSR(a1[3], aA1, 6144);
;   asm volatile("s_waitcnt lgkmcnt(6)" : "+v"(b0[0]), "+v"(b0[1]), "+v"(a0[0]), "+v"(a0[1]), "+v"(a0[2]), "+v"(a0[3]));
; #pragma unroll
;   for (int mi = 0; mi < 4; ++mi)
; #pragma unroll
;     for (int ni = 0; ni < 2; ++ni) {
;       if (VT) acc[mi][ni] = MFMA(a0[mi], b0[ni], acc[mi][ni]);
;       else acc[mi][ni] = MFMA(b0[ni], a0[mi], acc[mi][ni]);
;     }
;   __builtin_amdgcn_sched_barrier(0);
;   asm volatile("s_waitcnt lgkmcnt(0)" : "+v"(b1[0]), "+v"(b1[1]), "+v"(a1[0]), "+v"(a1[1]), "+v"(a1[2]), "+v"(a1[3]));
; #pragma unroll
;   for (int mi = 0; mi < 4; ++mi)
; #pragma unroll
;     for (int ni = 0; ni < 2; ++ni) {
;       if (VT) acc[mi][ni] = MFMA(a1[mi], b1[ni], acc[mi][ni]);
;       else acc[mi][ni] = MFMA(b1[ni], a1[mi], acc[mi][ni]);
;     }
; }
.LBB0_645:
	s_mul_i32 s56, s55, 0x3000
	v_lshl_add_u64 v[166:167], v[150:151], 0, s[46:47]
	s_mul_i32 s98, s55, 0x3000
	s_addk_i32 s98, 0xd000
	s_cmp_lg_u32 s55, 0
	s_cselect_b32 s98, s98, 0x6000
	s_lshl_b32 s98, s98, 1
	s_add_u32 s98, s98, s99
	s_mul_i32 s56, s55, 0x6000
	v_add_u32_e32 v174, s56, v159
	v_add_u32_e32 v32, s56, v157
	v_add_u32_e32 v198, s56, v160
	v_add_u32_e32 v202, s56, v158
	s_mov_b32 m0, s98
	s_waitcnt vmcnt(6)
	s_barrier
	global_load_lds_dwordx4 v[166:167], off
	ds_read_b128 v[166:169], v174 offset:0
	ds_read_b128 v[170:173], v174 offset:2048
	ds_read_b128 v[174:177], v32 offset:0
	ds_read_b128 v[178:181], v32 offset:2048
	ds_read_b128 v[182:185], v32 offset:4096
	ds_read_b128 v[186:189], v32 offset:6144
	ds_read_b128 v[190:193], v198 offset:0
	ds_read_b128 v[194:197], v198 offset:2048
	ds_read_b128 v[198:201], v202 offset:0
	ds_read_b128 v[204:207], v202 offset:2048
	ds_read_b128 v[244:247], v202 offset:4096
	ds_read_b128 v[248:251], v202 offset:6144
	s_waitcnt lgkmcnt(9)
	v_mfma_f32_32x32x16_bf16 v[98:113], v[166:169], v[174:177], v[98:113]
	v_mfma_f32_32x32x16_bf16 v[114:129], v[170:173], v[174:177], v[114:129]
	s_add_u32 m0, s98, 0x1000
	v_lshl_add_u64 v[216:217], v[148:149], 0, s[46:47]
	global_load_lds_dwordx4 v[216:217], off
	s_waitcnt lgkmcnt(8)
	v_mfma_f32_32x32x16_bf16 v[66:81], v[166:169], v[178:181], v[66:81]
	v_mfma_f32_32x32x16_bf16 v[82:97], v[170:173], v[178:181], v[82:97]
	s_add_u32 m0, s98, 0x2000
	v_lshl_add_u64 v[216:217], v[146:147], 0, s[46:47]
	global_load_lds_dwordx4 v[216:217], off
	s_waitcnt lgkmcnt(7)
	v_mfma_f32_32x32x16_bf16 v[34:49], v[166:169], v[182:185], v[34:49]
	v_mfma_f32_32x32x16_bf16 v[50:65], v[170:173], v[182:185], v[50:65]
	s_add_u32 m0, s98, 0x3000
	v_lshl_add_u64 v[216:217], v[144:145], 0, s[46:47]
	global_load_lds_dwordx4 v[216:217], off
	s_waitcnt lgkmcnt(6)
	v_mfma_f32_32x32x16_bf16 v[0:15], v[166:169], v[186:189], v[0:15]
	v_mfma_f32_32x32x16_bf16 v[16:31], v[170:173], v[186:189], v[16:31]
	s_add_u32 m0, s98, 0x4000
	v_lshl_add_u64 v[216:217], v[142:143], 0, s[46:47]
	global_load_lds_dwordx4 v[216:217], off
	s_waitcnt lgkmcnt(3)
	v_mfma_f32_32x32x16_bf16 v[98:113], v[190:193], v[198:201], v[98:113]
	v_mfma_f32_32x32x16_bf16 v[114:129], v[194:197], v[198:201], v[114:129]
	s_add_u32 m0, s98, 0x5000
	v_lshl_add_u64 v[216:217], v[140:141], 0, s[46:47]
	global_load_lds_dwordx4 v[216:217], off
	s_add_i32 s56, s55, 1
	s_cmp_lg_u32 s55, 2
	s_cselect_b32 s55, s56, 0
	s_add_u32 s46, s46, 64
	s_addc_u32 s47, s47, 0
	s_cmpk_eq_i32 s46, 0x780
	s_waitcnt lgkmcnt(2)
	v_mfma_f32_32x32x16_bf16 v[66:81], v[190:193], v[204:207], v[66:81]
	v_mfma_f32_32x32x16_bf16 v[82:97], v[194:197], v[204:207], v[82:97]
	s_waitcnt lgkmcnt(1)
	v_mfma_f32_32x32x16_bf16 v[34:49], v[190:193], v[244:247], v[34:49]
	v_mfma_f32_32x32x16_bf16 v[50:65], v[194:197], v[244:247], v[50:65]
	s_waitcnt lgkmcnt(0)
	v_mfma_f32_32x32x16_bf16 v[0:15], v[190:193], v[248:251], v[0:15]
	v_mfma_f32_32x32x16_bf16 v[16:31], v[194:197], v[248:251], v[16:31]
	s_cbranch_scc0 .LBB0_645
	v_mov_b32_e32 v216, 0x100
	v_mov_b32_e32 v217, 0x200
	s_mul_i32 s46, s55, 0x6000
	v_add_u32_e32 v148, s46, v159
	s_waitcnt vmcnt(6)
	s_barrier
; DI void dma_issue(const bf16_t* Ag, size_t lda, const bf16_t* Bg, size_t ldb, int kt, bf16_t* stage, int wid, int lane) {
;   const int rl = lane >> 2, c = (lane & 3) ^ ((lane >> 4) & 3);
; #pragma unroll
;   for (int i = 0; i < 4; ++i) {
;     const int j = wid + 4 * i;
;     __builtin_amdgcn_global_load_lds((const unsigned*)(Ag + (size_t)(16 * j + rl) * lda + kt * 32 + c * 8), (unsigned*)(stage + j * 512), 16, 0, 0);
;   }
; #pragma unroll
;   for (int i = 0; i < 2; ++i) {
;     const int j = wid + 4 * i;
;     __builtin_amdgcn_global_load_lds((const unsigned*)(Bg + (size_t)(16 * j + rl) * ldb + kt * 32 + c * 8), (unsigned*)(stage + STG_A + j * 512), 16, 0, 0);
;   }
; }
; template <bool VT>
; DI int gemm_kloop(const bf16_t* Ag, size_t lda, const bf16_t* Bg, size_t ldb, int nk, bf16_t* ring, f32x16 (&acc)[4][2], int tid, int wm, int wn,
;                   int r, int h, int st0, bool pre, const bf16_t* AgN, const bf16_t* BgN) {
;     ...
;   asm volatile("s_waitcnt vmcnt(0)" ::: "memory");
;   __builtin_amdgcn_s_barrier();
;   if (AgN) {
;     const int s1 = st == 2 ? 0 : st + 1, s2 = s1 == 2 ? 0 : s1 + 1;
;     dma_issue(AgN, lda, BgN, ldb, 0, ring + s1 * STG, wid, lane);
;     dma_issue(AgN, lda, BgN, ldb, 1, ring + s2 * STG, wid, lane);
;   }
;   {
;     const unsigned so = (unsigned)st * (unsigned)(STG * 2);
;     g_compute_asm<VT>(oA0 + so, oA1 + so, oB0 + so, oB1 + so, acc);
;   }
	v_add_u32_e32 v32, s46, v157
	v_add_u32_e32 v186, s46, v160
	ds_read_b128 v[140:143], v148 offset:0
	ds_read_b128 v[144:147], v148 offset:2048
	ds_read_b128 v[148:151], v32 offset:0
	ds_read_b128 v[166:169], v32 offset:2048
	ds_read_b128 v[170:173], v32 offset:4096
	ds_read_b128 v[174:177], v32 offset:6144
	v_add_u32_e32 v202, s46, v158
	ds_read_b128 v[178:181], v186 offset:0
	ds_read_b128 v[182:185], v186 offset:2048
	ds_read_b128 v[186:189], v202 offset:0
	ds_read_b128 v[190:193], v202 offset:2048
	ds_read_b128 v[194:197], v202 offset:4096
	ds_read_b128 v[198:201], v202 offset:6144
	s_waitcnt lgkmcnt(6)
	s_nop 0
	v_mfma_f32_32x32x16_bf16 v[98:113], v[140:143], v[148:151], v[98:113]
	v_mfma_f32_32x32x16_bf16 v[114:129], v[144:147], v[148:151], v[114:129]
	v_mfma_f32_32x32x16_bf16 v[66:81], v[140:143], v[166:169], v[66:81]
	v_mfma_f32_32x32x16_bf16 v[82:97], v[144:147], v[166:169], v[82:97]
	v_mfma_f32_32x32x16_bf16 v[34:49], v[140:143], v[170:173], v[34:49]
	v_mfma_f32_32x32x16_bf16 v[50:65], v[144:147], v[170:173], v[50:65]
	v_mfma_f32_32x32x16_bf16 v[0:15], v[140:143], v[174:177], v[0:15]
	v_mfma_f32_32x32x16_bf16 v[16:31], v[144:147], v[174:177], v[16:31]
	s_waitcnt lgkmcnt(0)
	s_add_i32 s46, s55, 1
	v_mfma_f32_32x32x16_bf16 v[98:113], v[178:181], v[186:189], v[98:113]
	s_waitcnt vmcnt(0)
	s_cmp_lg_u32 s55, 2
	s_cselect_b32 s67, s46, 0
	s_cmp_lg_u64 s[36:37], 0
	s_barrier
	v_mfma_f32_32x32x16_bf16 v[114:129], v[182:185], v[186:189], v[114:129]
	v_mfma_f32_32x32x16_bf16 v[66:81], v[178:181], v[190:193], v[66:81]
	v_mfma_f32_32x32x16_bf16 v[82:97], v[182:185], v[190:193], v[82:97]
	v_mfma_f32_32x32x16_bf16 v[34:49], v[178:181], v[194:197], v[34:49]
	v_mfma_f32_32x32x16_bf16 v[50:65], v[182:185], v[194:197], v[50:65]
	v_mfma_f32_32x32x16_bf16 v[0:15], v[178:181], v[198:201], v[0:15]
	v_mfma_f32_32x32x16_bf16 v[16:31], v[182:185], v[198:201], v[16:31]
	s_cbranch_scc0 .LBB0_648
	s_add_i32 s46, s67, 1
	s_cmp_lg_u32 s67, 2
	s_cselect_b32 s46, s46, 0
	s_mul_i32 s47, s46, 0x3000
	s_lshl_b32 s55, s47, 1
	v_lshlrev_b32_e32 v32, 1, v162
	v_add_u32_e32 v146, s55, v32
	v_lshlrev_b32_e32 v147, 1, v163
	v_lshl_add_u64 v[140:141], s[36:37], 0, v[138:139]
	v_lshlrev_b64 v[130:131], 1, v[130:131]
	v_readfirstlane_b32 s56, v146
	v_add_u32_e32 v148, s55, v147
	v_lshl_add_u64 v[142:143], v[140:141], 0, v[130:131]
	s_mov_b32 m0, s56
	v_lshlrev_b64 v[132:133], 1, v[132:133]
	v_readfirstlane_b32 s56, v148
	v_add_u32_e32 v149, s55, v165
	s_addk_i32 s47, 0x3000
	global_load_lds_dwordx4 v[142:143], off
	v_lshl_add_u64 v[144:145], v[140:141], 0, v[132:133]
	s_mov_b32 m0, s56
	v_lshl_add_u64 v[134:135], v[134:135], 1, v[140:141]
	v_readfirstlane_b32 s56, v149
	v_lshl_add_u64 v[136:137], v[136:137], 1, v[140:141]
	v_add_u32_e32 v140, s55, v164
	s_cmp_lg_u32 s46, 2
	global_load_lds_dwordx4 v[144:145], off
	s_mov_b32 m0, s56
	v_readfirstlane_b32 s55, v140
	v_lshl_add_u64 v[138:139], s[38:39], 0, v[138:139]
	v_add_u32_e32 v140, 0x4000, v146
	s_cselect_b32 s46, s47, 0
	global_load_lds_dwordx4 v[134:135], off
	s_mov_b32 m0, s55
	v_lshl_add_u64 v[130:131], v[138:139], 0, v[130:131]
	v_readfirstlane_b32 s55, v140
	v_lshl_add_u64 v[132:133], v[138:139], 0, v[132:133]
	v_add_u32_e32 v138, 0x4000, v148
	s_lshl_b32 s46, s46, 1
	global_load_lds_dwordx4 v[136:137], off
	s_mov_b32 m0, s55
	v_readfirstlane_b32 s55, v138
	v_add_u32_e32 v32, s46, v32
	global_load_lds_dwordx4 v[130:131], off
	s_mov_b32 m0, s55
	v_readfirstlane_b32 s47, v32
	v_add_u32_e32 v140, s46, v147
	global_load_lds_dwordx4 v[132:133], off
	v_lshl_add_u64 v[138:139], v[142:143], 0, 64
	s_mov_b32 m0, s47
	v_readfirstlane_b32 s47, v140
	global_load_lds_dwordx4 v[138:139], off
	v_lshl_add_u64 v[138:139], v[144:145], 0, 64
	s_mov_b32 m0, s47
	v_lshl_add_u64 v[134:135], v[134:135], 0, 64
	global_load_lds_dwordx4 v[138:139], off
	v_add_u32_e32 v138, s46, v165
	v_add_u32_e32 v32, 0x4000, v32
	v_readfirstlane_b32 s47, v138
	s_mov_b32 m0, s47
	v_lshl_add_u64 v[130:131], v[130:131], 0, 64
	global_load_lds_dwordx4 v[134:135], off
	v_lshl_add_u64 v[134:135], v[136:137], 0, 64
	v_add_u32_e32 v136, s46, v164
	s_nop 0
	v_readfirstlane_b32 s46, v136
	s_mov_b32 m0, s46
	v_readfirstlane_b32 s46, v32
	v_add_u32_e32 v32, 0x4000, v140
	global_load_lds_dwordx4 v[134:135], off
	s_mov_b32 m0, s46
	v_readfirstlane_b32 s46, v32
	global_load_lds_dwordx4 v[130:131], off
	v_lshl_add_u64 v[130:131], v[132:133], 0, 64
	s_mov_b32 m0, s46
	s_nop 0
	global_load_lds_dwordx4 v[130:131], off

; #define MFMA(a, b, c) __builtin_amdgcn_mfma_f32_32x32x16_bf16((a), (b), (c), 0, 0, 0)
; #define DSR(dst, addr, off) asm volatile("ds_read_b128 %0, %1 offset:" #off : "=&v"(dst) : "v"(addr))
; DI void dma_issue(const bf16_t* Ag, size_t lda, const bf16_t* Bg, size_t ldb, int kt, bf16_t* stage, int wid, int lane) {
;   const int rl = lane >> 2, c = (lane & 3) ^ ((lane >> 4) & 3);
; #pragma unroll
;   for (int i = 0; i < 4; ++i) {
;     const int j = wid + 4 * i;
;     __builtin_amdgcn_global_load_lds((const unsigned*)(Ag + (size_t)(16 * j + rl) * lda + kt * 32 + c * 8), (unsigned*)(stage + j * 512), 16, 0, 0);
;   }
; #pragma unroll
;   for (int i = 0; i < 2; ++i) {
;     const int j = wid + 4 * i;
;     __builtin_amdgcn_global_load_lds((const unsigned*)(Bg + (size_t)(16 * j + rl) * ldb + kt * 32 + c * 8), (unsigned*)(stage + STG_A + j * 512), 16, 0, 0);
;   }
; }
; template <bool VT>
; DI void g_compute_asm(unsigned aA0, unsigned aA1, unsigned aB0, unsigned aB1, f32x16 (&acc)[4][2]) {
;   bf16x8 a0[4], a1[4], b0[2], b1[2];
;   DSR(b0[0], aB0, 0); DSR(b0[1], aB0, 2048);
;   DSR(a0[0], aA0, 0); DSR(a0[1], aA0, 2048); DSR(a0[2], aA0, 4096); DSR(a0[3], aA0, 6144);
;   DSR(b1[0], aB1, 0); DSR(b1[1], aB1, 2048);
;   DSR(a1[0], aA1, 0); DSR(a1[1], aA1, 2048); DSR(a1[2], aA1, 4096); DSR(a1[3], aA1, 6144);
;   asm volatile("s_waitcnt lgkmcnt(6)" : "+v"(b0[0]), "+v"(b0[1]), "+v"(a0[0]), "+v"(a0[1]), "+v"(a0[2]), "+v"(a0[3]));
; #pragma unroll
;   for (int mi = 0; mi < 4; ++mi)
; #pragma unroll
;     for (int ni = 0; ni < 2; ++ni) {
;       if (VT) acc[mi][ni] = MFMA(a0[mi], b0[ni], acc[mi][ni]);
;       else acc[mi][ni] = MFMA(b0[ni], a0[mi], acc[mi][ni]);
;     }
;   __builtin_amdgcn_sched_barrier(0);
;   asm volatile("s_waitcnt lgkmcnt(0)" : "+v"(b1[0]), "+v"(b1[1]), "+v"(a1[0]), "+v"(a1[1]), "+v"(a1[2]), "+v"(a1[3]));
; #pragma unroll
;   for (int mi = 0; mi < 4; ++mi)
; #pragma unroll
;     for (int ni = 0; ni < 2; ++ni) {
;       if (VT) acc[mi][ni] = MFMA(a1[mi], b1[ni], acc[mi][ni]);
;       else acc[mi][ni] = MFMA(b1[ni], a1[mi], acc[mi][ni]);
;     }
; }
.LBB0_655:
	s_mul_i32 s42, s48, 0x3000
	v_lshl_add_u64 v[166:167], v[150:151], 0, s[40:41]
	s_mul_i32 s98, s48, 0x3000
	s_addk_i32 s98, 0xd000
	s_cmp_lg_u32 s48, 0
	s_cselect_b32 s98, s98, 0x6000
	s_lshl_b32 s98, s98, 1
	s_add_u32 s98, s98, s99
	s_mul_i32 s42, s48, 0x6000
	v_add_u32_e32 v174, s42, v159
	v_add_u32_e32 v32, s42, v157
	v_add_u32_e32 v198, s42, v160
	v_add_u32_e32 v165, s42, v158
	s_mov_b32 m0, s98
	s_waitcnt vmcnt(6)
	s_barrier
	global_load_lds_dwordx4 v[166:167], off
	ds_read_b128 v[166:169], v174 offset:0
	ds_read_b128 v[170:173], v174 offset:2048
	ds_read_b128 v[174:177], v32 offset:0
	ds_read_b128 v[178:181], v32 offset:2048
	ds_read_b128 v[182:185], v32 offset:4096
	ds_read_b128 v[186:189], v32 offset:6144
	ds_read_b128 v[190:193], v198 offset:0
	ds_read_b128 v[194:197], v198 offset:2048
	ds_read_b128 v[198:201], v165 offset:0
	ds_read_b128 v[244:247], v165 offset:2048
	ds_read_b128 v[248:251], v165 offset:4096
	ds_read_b128 v[204:207], v165 offset:6144
	s_waitcnt lgkmcnt(9)
	v_mfma_f32_32x32x16_bf16 v[98:113], v[174:177], v[166:169], v[98:113]
	v_mfma_f32_32x32x16_bf16 v[114:129], v[174:177], v[170:173], v[114:129]
	s_add_u32 m0, s98, 0x1000
	v_lshl_add_u64 v[216:217], v[148:149], 0, s[40:41]
	global_load_lds_dwordx4 v[216:217], off
	s_waitcnt lgkmcnt(8)
	v_mfma_f32_32x32x16_bf16 v[66:81], v[178:181], v[166:169], v[66:81]
	v_mfma_f32_32x32x16_bf16 v[82:97], v[178:181], v[170:173], v[82:97]
	s_add_u32 m0, s98, 0x2000
	v_lshl_add_u64 v[216:217], v[146:147], 0, s[40:41]
	global_load_lds_dwordx4 v[216:217], off
	s_waitcnt lgkmcnt(7)
	v_mfma_f32_32x32x16_bf16 v[34:49], v[182:185], v[166:169], v[34:49]
	v_mfma_f32_32x32x16_bf16 v[50:65], v[182:185], v[170:173], v[50:65]
	s_add_u32 m0, s98, 0x3000
	v_lshl_add_u64 v[216:217], v[144:145], 0, s[40:41]
	global_load_lds_dwordx4 v[216:217], off
	s_waitcnt lgkmcnt(6)
	v_mfma_f32_32x32x16_bf16 v[0:15], v[186:189], v[166:169], v[0:15]
	v_mfma_f32_32x32x16_bf16 v[16:31], v[186:189], v[170:173], v[16:31]
	s_add_u32 m0, s98, 0x4000
	v_lshl_add_u64 v[216:217], v[142:143], 0, s[40:41]
	global_load_lds_dwordx4 v[216:217], off
	s_waitcnt lgkmcnt(3)
	v_mfma_f32_32x32x16_bf16 v[98:113], v[198:201], v[190:193], v[98:113]
	v_mfma_f32_32x32x16_bf16 v[114:129], v[198:201], v[194:197], v[114:129]
	s_add_u32 m0, s98, 0x5000
	v_lshl_add_u64 v[216:217], v[140:141], 0, s[40:41]
	global_load_lds_dwordx4 v[216:217], off
	s_add_i32 s42, s48, 1
	s_cmp_lg_u32 s48, 2
	s_cselect_b32 s48, s42, 0
	s_add_u32 s40, s40, 64
	s_addc_u32 s41, s41, 0
	s_cmpk_eq_i32 s40, 0x780
	s_waitcnt lgkmcnt(2)
	v_mfma_f32_32x32x16_bf16 v[66:81], v[244:247], v[190:193], v[66:81]
	v_mfma_f32_32x32x16_bf16 v[82:97], v[244:247], v[194:197], v[82:97]
	s_waitcnt lgkmcnt(1)
	v_mfma_f32_32x32x16_bf16 v[34:49], v[248:251], v[190:193], v[34:49]
	v_mfma_f32_32x32x16_bf16 v[50:65], v[248:251], v[194:197], v[50:65]
	s_waitcnt lgkmcnt(0)
	v_mfma_f32_32x32x16_bf16 v[0:15], v[204:207], v[190:193], v[0:15]
	v_mfma_f32_32x32x16_bf16 v[16:31], v[204:207], v[194:197], v[16:31]
	s_cbranch_scc0 .LBB0_655
	v_mov_b32_e32 v216, 0x100
	v_mov_b32_e32 v217, 0x200
	s_mul_i32 s40, s48, 0x6000
	v_add_u32_e32 v148, s40, v159
	s_waitcnt vmcnt(6)
	s_barrier
; DI void dma_issue(const bf16_t* Ag, size_t lda, const bf16_t* Bg, size_t ldb, int kt, bf16_t* stage, int wid, int lane) {
;   const int rl = lane >> 2, c = (lane & 3) ^ ((lane >> 4) & 3);
; #pragma unroll
;   for (int i = 0; i < 4; ++i) {
;     const int j = wid + 4 * i;
;     __builtin_amdgcn_global_load_lds((const unsigned*)(Ag + (size_t)(16 * j + rl) * lda + kt * 32 + c * 8), (unsigned*)(stage + j * 512), 16, 0, 0);
;   }
; #pragma unroll
;   for (int i = 0; i < 2; ++i) {
;     const int j = wid + 4 * i;
;     __builtin_amdgcn_global_load_lds((const unsigned*)(Bg + (size_t)(16 * j + rl) * ldb + kt * 32 + c * 8), (unsigned*)(stage + STG_A + j * 512), 16, 0, 0);
;   }
; }
; template <bool VT>
; DI int gemm_kloop(const bf16_t* Ag, size_t lda, const bf16_t* Bg, size_t ldb, int nk, bf16_t* ring, f32x16 (&acc)[4][2], int tid, int wm, int wn,
;                   int r, int h, int st0, bool pre, const bf16_t* AgN, const bf16_t* BgN) {
;     ...
;   asm volatile("s_waitcnt vmcnt(0)" ::: "memory");
;   __builtin_amdgcn_s_barrier();
;   if (AgN) {
;     const int s1 = st == 2 ? 0 : st + 1, s2 = s1 == 2 ? 0 : s1 + 1;
;     dma_issue(AgN, lda, BgN, ldb, 0, ring + s1 * STG, wid, lane);
;     dma_issue(AgN, lda, BgN, ldb, 1, ring + s2 * STG, wid, lane);
;   }
;   {
;     const unsigned so = (unsigned)st * (unsigned)(STG * 2);
;     g_compute_asm<VT>(oA0 + so, oA1 + so, oB0 + so, oB1 + so, acc);
;   }
	v_add_u32_e32 v32, s40, v157
	v_add_u32_e32 v186, s40, v160
	ds_read_b128 v[140:143], v148 offset:0
	ds_read_b128 v[144:147], v148 offset:2048
	ds_read_b128 v[148:151], v32 offset:0
	ds_read_b128 v[166:169], v32 offset:2048
	ds_read_b128 v[170:173], v32 offset:4096
	ds_read_b128 v[174:177], v32 offset:6144
	v_add_u32_e32 v165, s40, v158
	ds_read_b128 v[178:181], v186 offset:0
	ds_read_b128 v[182:185], v186 offset:2048
	ds_read_b128 v[186:189], v165 offset:0
	ds_read_b128 v[190:193], v165 offset:2048
	ds_read_b128 v[194:197], v165 offset:4096
	ds_read_b128 v[198:201], v165 offset:6144
	s_waitcnt lgkmcnt(6)
	s_nop 0
	v_mfma_f32_32x32x16_bf16 v[98:113], v[148:151], v[140:143], v[98:113]
	v_mfma_f32_32x32x16_bf16 v[114:129], v[148:151], v[144:147], v[114:129]
	v_mfma_f32_32x32x16_bf16 v[66:81], v[166:169], v[140:143], v[66:81]
	v_mfma_f32_32x32x16_bf16 v[82:97], v[166:169], v[144:147], v[82:97]
	v_mfma_f32_32x32x16_bf16 v[34:49], v[170:173], v[140:143], v[34:49]
	v_mfma_f32_32x32x16_bf16 v[50:65], v[170:173], v[144:147], v[50:65]
	v_mfma_f32_32x32x16_bf16 v[0:15], v[174:177], v[140:143], v[0:15]
	v_mfma_f32_32x32x16_bf16 v[16:31], v[174:177], v[144:147], v[16:31]
	s_waitcnt lgkmcnt(0)
	s_add_i32 s40, s48, 1
	v_mfma_f32_32x32x16_bf16 v[98:113], v[186:189], v[178:181], v[98:113]
	s_waitcnt vmcnt(0)
	s_cmp_lg_u32 s48, 2
	s_cselect_b32 s67, s40, 0
	s_cmp_lg_u64 s[36:37], 0
	s_barrier
	v_mfma_f32_32x32x16_bf16 v[114:129], v[186:189], v[182:185], v[114:129]
	v_mfma_f32_32x32x16_bf16 v[66:81], v[190:193], v[178:181], v[66:81]
	v_mfma_f32_32x32x16_bf16 v[82:97], v[190:193], v[182:185], v[82:97]
	v_mfma_f32_32x32x16_bf16 v[34:49], v[194:197], v[178:181], v[34:49]
	v_mfma_f32_32x32x16_bf16 v[50:65], v[194:197], v[182:185], v[50:65]
	v_mfma_f32_32x32x16_bf16 v[0:15], v[198:201], v[178:181], v[0:15]
	v_mfma_f32_32x32x16_bf16 v[16:31], v[198:201], v[182:185], v[16:31]
	s_cbranch_scc0 .LBB0_658
	s_add_i32 s40, s67, 1
	s_cmp_lg_u32 s67, 2
	s_cselect_b32 s40, s40, 0
	s_mul_i32 s41, s40, 0x3000
	s_lshl_b32 s42, s41, 1
	v_lshlrev_b32_e32 v32, 1, v162
	v_add_u32_e32 v146, s42, v32
	v_lshlrev_b32_e32 v147, 1, v161
	v_lshl_add_u64 v[140:141], s[36:37], 0, v[138:139]
	v_lshlrev_b64 v[130:131], 1, v[130:131]
	v_readfirstlane_b32 s36, v146
	v_add_u32_e32 v148, s42, v147
	v_lshl_add_u64 v[142:143], v[140:141], 0, v[130:131]
	s_mov_b32 m0, s36
	v_lshlrev_b64 v[132:133], 1, v[132:133]
	v_readfirstlane_b32 s36, v148
	v_add_u32_e32 v149, s42, v164
	global_load_lds_dwordx4 v[142:143], off
	v_lshl_add_u64 v[144:145], v[140:141], 0, v[132:133]
	s_mov_b32 m0, s36
	v_lshl_add_u64 v[134:135], v[134:135], 1, v[140:141]
	v_readfirstlane_b32 s36, v149
	v_lshl_add_u64 v[136:137], v[136:137], 1, v[140:141]
	v_add_u32_e32 v140, s42, v163
	global_load_lds_dwordx4 v[144:145], off
	s_mov_b32 m0, s36
	v_readfirstlane_b32 s36, v140
	v_lshl_add_u64 v[138:139], s[38:39], 0, v[138:139]
	v_add_u32_e32 v140, 0x4000, v146
	global_load_lds_dwordx4 v[134:135], off
	s_mov_b32 m0, s36
	v_lshl_add_u64 v[130:131], v[138:139], 0, v[130:131]
	v_readfirstlane_b32 s36, v140
	v_lshl_add_u64 v[132:133], v[138:139], 0, v[132:133]
	v_add_u32_e32 v138, 0x4000, v148
	s_addk_i32 s41, 0x3000
	global_load_lds_dwordx4 v[136:137], off
	s_mov_b32 m0, s36
	v_readfirstlane_b32 s36, v138
	s_cmp_lg_u32 s40, 2
	global_load_lds_dwordx4 v[130:131], off
	s_mov_b32 m0, s36
	s_cselect_b32 s36, s41, 0
	s_lshl_b32 s36, s36, 1
	v_add_u32_e32 v32, s36, v32
	v_add_u32_e32 v140, s36, v147
	v_readfirstlane_b32 s37, v32
	global_load_lds_dwordx4 v[132:133], off
	v_lshl_add_u64 v[138:139], v[142:143], 0, 64
	s_mov_b32 m0, s37
	v_readfirstlane_b32 s37, v140
	global_load_lds_dwordx4 v[138:139], off
	v_lshl_add_u64 v[138:139], v[144:145], 0, 64
	s_mov_b32 m0, s37
	v_lshl_add_u64 v[134:135], v[134:135], 0, 64
	global_load_lds_dwordx4 v[138:139], off
	v_add_u32_e32 v138, s36, v164
	v_add_u32_e32 v32, 0x4000, v32
	v_readfirstlane_b32 s37, v138
	s_mov_b32 m0, s37
	v_lshl_add_u64 v[130:131], v[130:131], 0, 64
	global_load_lds_dwordx4 v[134:135], off
	v_lshl_add_u64 v[134:135], v[136:137], 0, 64
	v_add_u32_e32 v136, s36, v163
	s_nop 0
	v_readfirstlane_b32 s36, v136
	s_mov_b32 m0, s36
	v_readfirstlane_b32 s36, v32
	v_add_u32_e32 v32, 0x4000, v140
	global_load_lds_dwordx4 v[134:135], off
	s_mov_b32 m0, s36
	v_readfirstlane_b32 s36, v32
	global_load_lds_dwordx4 v[130:131], off
	v_lshl_add_u64 v[130:131], v[132:133], 0, 64
	s_mov_b32 m0, s36
	s_nop 0
	global_load_lds_dwordx4 v[130:131], off

; template <bool VT>
; DI int gemm_kloop(const bf16_t* Ag, size_t lda, const bf16_t* Bg, size_t ldb, int nk, bf16_t* ring, f32x16 (&acc)[4][2], int tid, int wm, int wn,
;                   int r, int h, int st0, bool pre, const bf16_t* AgN, const bf16_t* BgN) {
;   const int wid = tid >> 6, lane = tid & 63;
;   const unsigned base = (unsigned)(unsigned long long)ring;
;   const int q = (r >> 2) & 3;
;   const unsigned rA = base + (unsigned)(wm * 128 + r) * 64u, rB = base + (unsigned)STG_A * 2u + (unsigned)(wn * 64 + r) * 64u;
;   const unsigned oA0 = rA + (unsigned)((h ^ q) & 3) * 16u, oA1 = rA + (unsigned)(((2 + h) ^ q) & 3) * 16u;
;   const unsigned oB0 = rB + (unsigned)((h ^ q) & 3) * 16u, oB1 = rB + (unsigned)(((2 + h) ^ q) & 3) * 16u;
;   int st = st0;
;   if (!pre) {
;     dma_issue(Ag, lda, Bg, ldb, 0, ring + st * STG, wid, lane);
;     dma_issue(Ag, lda, Bg, ldb, 1, ring + (st == 2 ? 0 : st + 1) * STG, wid, lane);
;   }
;     ...
;   f32x16 acc[4][2];
; #pragma unroll
;   for (int a = 0; a < 4; ++a)
; #pragma unroll
;     for (int b = 0; b < 2; ++b)
; #pragma unroll
;       for (int i = 0; i < 16; ++i) acc[a][b][i] = 0.f;
.LBB0_1136:
	s_ashr_i32 s11, s20, 31
	s_ashr_i32 s10, s20, 3
	s_lshr_b32 s11, s11, 26
	s_add_i32 s11, s10, s11
	s_ashr_i32 s29, s11, 6
	s_andn2_b32 s11, s11, 63
	s_sub_i32 s10, s10, s11
	s_and_b32 s11, s20, 7
	s_add_i32 s11, s29, s11
	v_mov_b32_e32 v144, v242
	s_lshl_b32 s22, s10, 8
	s_lshl_b32 s10, s10, 4
	s_lshl_b32 s11, s11, 11
	v_ashrrev_i32_e32 v145, 6, v144
	s_and_b32 s30, s22, 0x700
	s_and_b32 s23, s10, 0xffffff80
	v_bfe_u32 v143, v144, 5, 1
	s_or_b32 s22, s11, s30
	s_mul_i32 s10, s23, 0x440
	s_waitcnt vmcnt(0)
	v_and_b32_e32 v146, 31, v144
	v_and_b32_e32 v151, 1, v145
	v_lshrrev_b32_e32 v0, 2, v144
	s_and_b32 s28, s19, 7
	s_ashr_i32 s11, s10, 31
	s_mul_i32 s24, s22, 0x880
	v_lshlrev_b32_e32 v2, 6, v144
	v_lshlrev_b32_e32 v3, 6, v146
	v_lshlrev_b32_e32 v4, 12, v151
	v_bitop3_b32 v0, v0, v143, 3 bitop3:0x6c
	s_mul_hi_i32 s25, s22, 0x880
	s_add_u32 s24, s12, s24
	v_bfe_u32 v1, v144, 2, 2
	v_and_or_b32 v2, v2, s93, v3
	v_or3_b32 v3, v3, v4, s94
	v_lshlrev_b32_e32 v0, 4, v0
	v_bfe_u32 v142, v144, 4, 2
	s_addc_u32 s25, s13, s25
	s_lshl_b64 s[10:11], s[10:11], 1
	v_or_b32_e32 v147, v0, v2
	v_bitop3_b32 v1, v143, v1, 2 bitop3:0x36
	v_or_b32_e32 v149, v3, v0
	v_bitop3_b32 v0, v142, v144, 3 bitop3:0x78
	s_add_u32 s26, s14, s10
	v_lshlrev_b32_e32 v1, 4, v1
	s_mul_i32 s31, s21, 0x3000
	v_bfe_u32 v8, v144, 2, 4
	v_lshlrev_b32_e32 v32, 4, v0
	s_addc_u32 s27, s15, s11
	v_or_b32_e32 v148, v1, v2
	v_or_b32_e32 v150, v1, v3
	s_lshl_b32 s33, s31, 1
	v_lshl_add_u64 v[0:1], s[24:25], 0, v[32:33]
	v_lshl_or_b32 v12, v145, 4, v8
	v_lshlrev_b32_e32 v13, 10, v145
	v_mad_i64_i32 v[2:3], s[24:25], v12, s74, v[0:1]
	v_add_u32_e32 v14, s33, v13
	v_add_u32_e32 v6, 4, v145
	v_readfirstlane_b32 s24, v14
	v_lshl_or_b32 v15, v6, 4, v8
	v_lshlrev_b32_e32 v16, 10, v6
	s_mov_b32 m0, s24
	v_mad_i64_i32 v[4:5], s[24:25], v15, s74, v[0:1]
	v_add_u32_e32 v17, s33, v16
	v_add_u32_e32 v9, 8, v145
	v_lshlrev_b32_e32 v153, 9, v6
	v_readfirstlane_b32 s24, v17
	v_lshl_or_b32 v6, v9, 4, v8
	v_lshlrev_b32_e32 v154, 10, v9
	s_waitcnt lgkmcnt(0)
	s_barrier
	global_load_lds_dwordx4 v[2:3], off
	s_mov_b32 m0, s24
	v_mad_i64_i32 v[6:7], s[24:25], v6, s74, v[0:1]
	v_add_u32_e32 v9, s33, v154
	global_load_lds_dwordx4 v[4:5], off
	v_readfirstlane_b32 s24, v9
	v_add_u32_e32 v9, 12, v145
	v_lshl_or_b32 v8, v9, 4, v8
	v_lshlrev_b32_e32 v155, 10, v9
	s_mov_b32 m0, s24
	v_mad_i64_i32 v[0:1], s[24:25], v8, s74, v[0:1]
	v_add_u32_e32 v8, s33, v155
	global_load_lds_dwordx4 v[6:7], off
	v_readfirstlane_b32 s24, v8
	v_lshl_add_u64 v[8:9], s[26:27], 0, v[32:33]
	s_mov_b32 m0, s24
	v_mad_i64_i32 v[10:11], s[24:25], v12, s74, v[8:9]
	v_add_u32_e32 v14, 0x4000, v14
	global_load_lds_dwordx4 v[0:1], off
	v_readfirstlane_b32 s24, v14
	s_mov_b32 m0, s24
	v_mad_i64_i32 v[8:9], s[24:25], v15, s74, v[8:9]
	v_add_u32_e32 v14, 0x4000, v17
	s_addk_i32 s31, 0x3000
	v_readfirstlane_b32 s24, v14
	s_cmp_lg_u32 s21, 2
	global_load_lds_dwordx4 v[10:11], off
	s_mov_b32 m0, s24
	s_cselect_b32 s24, s31, 0
	s_lshl_b32 s24, s24, 1
	v_add_u32_e32 v13, s24, v13
	global_load_lds_dwordx4 v[8:9], off
	v_readfirstlane_b32 s25, v13
	v_lshl_add_u64 v[2:3], v[2:3], 0, 64
	s_mov_b32 m0, s25
	v_lshl_add_u64 v[0:1], v[0:1], 0, 64
	global_load_lds_dwordx4 v[2:3], off
	v_lshl_add_u64 v[2:3], v[4:5], 0, 64
	v_add_u32_e32 v4, s24, v16
	v_add_u32_e32 v5, s24, v154
	v_readfirstlane_b32 s25, v4
	s_mov_b32 m0, s25
	v_readfirstlane_b32 s25, v5
	global_load_lds_dwordx4 v[2:3], off
	v_lshl_add_u64 v[2:3], v[6:7], 0, 64
	s_mov_b32 m0, s25
	s_add_u32 s10, s17, s10
	global_load_lds_dwordx4 v[2:3], off
	v_add_u32_e32 v2, s24, v155
	s_addc_u32 s11, s18, s11
	v_readfirstlane_b32 s24, v2
	v_add_u32_e32 v2, 0x4000, v13
	s_mov_b32 m0, s24
	v_readfirstlane_b32 s24, v2
	v_add_u32_e32 v2, 0x4000, v4
	global_load_lds_dwordx4 v[0:1], off
	v_lshl_add_u64 v[0:1], v[10:11], 0, 64
	s_mov_b32 m0, s24
	v_readfirstlane_b32 s24, v2
	global_load_lds_dwordx4 v[0:1], off
	v_lshl_add_u64 v[0:1], v[8:9], 0, 64
	s_mov_b32 m0, s24
	v_mad_i64_i32 v[2:3], s[24:25], v12, s74, 0
	global_load_lds_dwordx4 v[0:1], off
	v_add_u32_e32 v0, 64, v12
	v_mad_i64_i32 v[0:1], s[24:25], v0, s74, 0
	v_or_b32_e32 v0, v0, v32
	v_or_b32_e32 v2, v2, v32
	s_add_i32 s29, s29, s28
	v_lshl_add_u64 v[130:131], s[10:11], 0, v[0:1]
	v_lshl_add_u64 v[132:133], s[10:11], 0, v[2:3]
	s_lshl_b32 s10, s29, 11
	s_or_b32 s24, s10, s30
	s_mul_hi_i32 s11, s24, 0x880
	s_mul_i32 s10, s24, 0x880
	v_add_u32_e32 v6, 0xc0, v12
	v_mov_b64_e32 v[4:5], s[10:11]
	v_mad_i64_i32 v[6:7], s[10:11], v6, s74, v[4:5]
	v_or_b32_e32 v6, v6, v32
	v_lshl_add_u64 v[134:135], s[8:9], 0, v[6:7]
	v_add_u32_e32 v6, 0x80, v12
	v_mad_i64_i32 v[0:1], s[10:11], s24, v211, v[0:1]
	v_mad_i64_i32 v[4:5], s[10:11], v6, s74, v[4:5]
	v_lshl_add_u64 v[138:139], s[8:9], 0, v[0:1]
	v_mad_i64_i32 v[0:1], s[10:11], s24, v211, v[2:3]
	v_or_b32_e32 v4, v4, v32
	v_lshl_add_u64 v[140:141], s[8:9], 0, v[0:1]
	v_mov_b32_e32 v0, 0
	v_lshlrev_b32_e32 v152, 9, v145
	v_lshl_add_u64 v[136:137], s[8:9], 0, v[4:5]
	s_mov_b64 s[10:11], 0
	v_mov_b32_e32 v1, v0
	v_mov_b32_e32 v2, v0
	v_mov_b32_e32 v3, v0
	v_mov_b32_e32 v4, v0
	v_mov_b32_e32 v5, v0
	v_mov_b32_e32 v6, v0
	v_mov_b32_e32 v7, v0
	v_mov_b32_e32 v8, v0
	v_mov_b32_e32 v9, v0
	v_mov_b32_e32 v10, v0
	v_mov_b32_e32 v11, v0
	v_mov_b32_e32 v12, v0
	v_mov_b32_e32 v13, v0
	v_mov_b32_e32 v14, v0
	v_mov_b32_e32 v15, v0
	v_mov_b32_e32 v16, v0
	v_mov_b32_e32 v17, v0
	v_mov_b32_e32 v18, v0
	v_mov_b32_e32 v19, v0
	v_mov_b32_e32 v20, v0
	v_mov_b32_e32 v21, v0
	v_mov_b32_e32 v22, v0
	v_mov_b32_e32 v23, v0
	v_mov_b32_e32 v24, v0
	v_mov_b32_e32 v25, v0
	v_mov_b32_e32 v26, v0
	v_mov_b32_e32 v27, v0
	v_mov_b32_e32 v28, v0
; #define MFMA(a, b, c) __builtin_amdgcn_mfma_f32_32x32x16_bf16((a), (b), (c), 0, 0, 0)
; #define DSR(dst, addr, off) asm volatile("ds_read_b128 %0, %1 offset:" #off : "=&v"(dst) : "v"(addr))
; DI void dma_issue(const bf16_t* Ag, size_t lda, const bf16_t* Bg, size_t ldb, int kt, bf16_t* stage, int wid, int lane) {
;   const int rl = lane >> 2, c = (lane & 3) ^ ((lane >> 4) & 3);
; #pragma unroll
;   for (int i = 0; i < 4; ++i) {
;     const int j = wid + 4 * i;
;     __builtin_amdgcn_global_load_lds((const unsigned*)(Ag + (size_t)(16 * j + rl) * lda + kt * 32 + c * 8), (unsigned*)(stage + j * 512), 16, 0, 0);
;   }
; #pragma unroll
;   for (int i = 0; i < 2; ++i) {
;     const int j = wid + 4 * i;
;     __builtin_amdgcn_global_load_lds((const unsigned*)(Bg + (size_t)(16 * j + rl) * ldb + kt * 32 + c * 8), (unsigned*)(stage + STG_A + j * 512), 16, 0, 0);
;   }
; }
; template <bool VT>
; DI void g_compute_asm(unsigned aA0, unsigned aA1, unsigned aB0, unsigned aB1, f32x16 (&acc)[4][2]) {
;   bf16x8 a0[4], a1[4], b0[2], b1[2];
;   DSR(b0[0], aB0, 0); DSR(b0[1], aB0, 2048);
;   DSR(a0[0], aA0, 0); DSR(a0[1], aA0, 2048); DSR(a0[2], aA0, 4096); DSR(a0[3], aA0, 6144);
;   DSR(b1[0], aB1, 0); DSR(b1[1], aB1, 2048);
;   DSR(a1[0], aA1, 0); DSR(a1[1], aA1, 2048); DSR(a1[2], aA1, 4096); DSR(a1[3], aA1, 6144);
;   asm volatile("s_waitcnt lgkmcnt(6)" : "+v"(b0[0]), "+v"(b0[1]), "+v"(a0[0]), "+v"(a0[1]), "+v"(a0[2]), "+v"(a0[3]));
; #pragma unroll
;   for (int mi = 0; mi < 4; ++mi)
; #pragma unroll
;     for (int ni = 0; ni < 2; ++ni) {
;       if (VT) acc[mi][ni] = MFMA(a0[mi], b0[ni], acc[mi][ni]);
;       else acc[mi][ni] = MFMA(b0[ni], a0[mi], acc[mi][ni]);
;     }
;   __builtin_amdgcn_sched_barrier(0);
;   asm volatile("s_waitcnt lgkmcnt(0)" : "+v"(b1[0]), "+v"(b1[1]), "+v"(a1[0]), "+v"(a1[1]), "+v"(a1[2]), "+v"(a1[3]));
; #pragma unroll
;   for (int mi = 0; mi < 4; ++mi)
; #pragma unroll
;     for (int ni = 0; ni < 2; ++ni) {
;       if (VT) acc[mi][ni] = MFMA(a1[mi], b1[ni], acc[mi][ni]);
;       else acc[mi][ni] = MFMA(b1[ni], a1[mi], acc[mi][ni]);
;     }
; }
	v_mov_b32_e32 v29, v0
	v_mov_b32_e32 v30, v0
	v_mov_b32_e32 v31, v0
	v_mov_b32_e32 v34, v0
	v_mov_b32_e32 v35, v0
	v_mov_b32_e32 v36, v0
	v_mov_b32_e32 v37, v0
	v_mov_b32_e32 v38, v0
	v_mov_b32_e32 v39, v0
	v_mov_b32_e32 v40, v0
	v_mov_b32_e32 v41, v0
	v_mov_b32_e32 v42, v0
	v_mov_b32_e32 v43, v0
	v_mov_b32_e32 v44, v0
	v_mov_b32_e32 v45, v0
	v_mov_b32_e32 v46, v0
	v_mov_b32_e32 v47, v0
	v_mov_b32_e32 v48, v0
	v_mov_b32_e32 v49, v0
	v_mov_b32_e32 v50, v0
	v_mov_b32_e32 v51, v0
	v_mov_b32_e32 v52, v0
	v_mov_b32_e32 v53, v0
	v_mov_b32_e32 v54, v0
	v_mov_b32_e32 v55, v0
	v_mov_b32_e32 v56, v0
	v_mov_b32_e32 v57, v0
	v_mov_b32_e32 v58, v0
	v_mov_b32_e32 v59, v0
	v_mov_b32_e32 v60, v0
	v_mov_b32_e32 v61, v0
	v_mov_b32_e32 v62, v0
	v_mov_b32_e32 v63, v0
	v_mov_b32_e32 v64, v0
	v_mov_b32_e32 v65, v0
	v_mov_b32_e32 v66, v0
	v_mov_b32_e32 v67, v0
	v_mov_b32_e32 v68, v0
	v_mov_b32_e32 v69, v0
	v_mov_b32_e32 v70, v0
	v_mov_b32_e32 v71, v0
	v_mov_b32_e32 v72, v0
	v_mov_b32_e32 v73, v0
	v_mov_b32_e32 v74, v0
	v_mov_b32_e32 v75, v0
	v_mov_b32_e32 v76, v0
	v_mov_b32_e32 v77, v0
	v_mov_b32_e32 v78, v0
	v_mov_b32_e32 v79, v0
	v_mov_b32_e32 v80, v0
	v_mov_b32_e32 v81, v0
	v_mov_b32_e32 v82, v0
	v_mov_b32_e32 v83, v0
	v_mov_b32_e32 v84, v0
	v_mov_b32_e32 v85, v0
	v_mov_b32_e32 v86, v0
	v_mov_b32_e32 v87, v0
	v_mov_b32_e32 v88, v0
	v_mov_b32_e32 v89, v0
	v_mov_b32_e32 v90, v0
	v_mov_b32_e32 v91, v0
	v_mov_b32_e32 v92, v0
	v_mov_b32_e32 v93, v0
	v_mov_b32_e32 v94, v0
	v_mov_b32_e32 v95, v0
	v_mov_b32_e32 v96, v0
	v_mov_b32_e32 v97, v0
	v_mov_b32_e32 v98, v0
	v_mov_b32_e32 v99, v0
	v_mov_b32_e32 v100, v0
	v_mov_b32_e32 v101, v0
	v_mov_b32_e32 v102, v0
	v_mov_b32_e32 v103, v0
	v_mov_b32_e32 v104, v0
	v_mov_b32_e32 v105, v0
	v_mov_b32_e32 v106, v0
	v_mov_b32_e32 v107, v0
	v_mov_b32_e32 v108, v0
	v_mov_b32_e32 v109, v0
	v_mov_b32_e32 v110, v0
	v_mov_b32_e32 v111, v0
	v_mov_b32_e32 v112, v0
	v_mov_b32_e32 v113, v0
	v_mov_b32_e32 v114, v0
	v_mov_b32_e32 v115, v0
	v_mov_b32_e32 v116, v0
	v_mov_b32_e32 v117, v0
	v_mov_b32_e32 v118, v0
	v_mov_b32_e32 v119, v0
	v_mov_b32_e32 v120, v0
	v_mov_b32_e32 v121, v0
	v_mov_b32_e32 v122, v0
	v_mov_b32_e32 v123, v0
	v_mov_b32_e32 v124, v0
	v_mov_b32_e32 v125, v0
	v_mov_b32_e32 v126, v0
	v_mov_b32_e32 v127, v0
	v_mov_b32_e32 v128, v0
	v_mov_b32_e32 v129, v0
	v_readfirstlane_b32 s99, v152
	s_lshl_b32 s99, s99, 1
.LBB0_1137:
	s_mul_i32 s24, s21, 0x3000
	v_lshl_add_u64 v[156:157], v[140:141], 0, s[10:11]
	s_mul_i32 s98, s21, 0x3000
	s_addk_i32 s98, 0xd000
	s_cmp_lg_u32 s21, 0
	s_cselect_b32 s98, s98, 0x6000
	s_lshl_b32 s98, s98, 1
	s_add_u32 s98, s98, s99
	s_mul_i32 s24, s21, 0x6000
	v_add_u32_e32 v164, s24, v149
	v_add_u32_e32 v32, s24, v147
	v_add_u32_e32 v188, s24, v150
	v_add_u32_e32 v200, s24, v148
	s_mov_b32 m0, s98
	s_waitcnt vmcnt(6)
	s_barrier
	global_load_lds_dwordx4 v[156:157], off
	ds_read_b128 v[156:159], v164 offset:0
	ds_read_b128 v[160:163], v164 offset:2048
	ds_read_b128 v[164:167], v32 offset:0
	ds_read_b128 v[168:171], v32 offset:2048
	ds_read_b128 v[172:175], v32 offset:4096
	ds_read_b128 v[176:179], v32 offset:6144
	ds_read_b128 v[180:183], v188 offset:0
	ds_read_b128 v[184:187], v188 offset:2048
	ds_read_b128 v[188:191], v200 offset:0
	ds_read_b128 v[192:195], v200 offset:2048
	ds_read_b128 v[196:199], v200 offset:4096
	ds_read_b128 v[204:207], v200 offset:6144
	s_waitcnt lgkmcnt(9)
	v_mfma_f32_32x32x16_bf16 v[114:129], v[156:159], v[164:167], v[114:129]
	v_mfma_f32_32x32x16_bf16 v[98:113], v[160:163], v[164:167], v[98:113]
	s_add_u32 m0, s98, 0x1000
	v_lshl_add_u64 v[202:203], v[138:139], 0, s[10:11]
	global_load_lds_dwordx4 v[202:203], off
	s_waitcnt lgkmcnt(8)
	v_mfma_f32_32x32x16_bf16 v[82:97], v[156:159], v[168:171], v[82:97]
	v_mfma_f32_32x32x16_bf16 v[66:81], v[160:163], v[168:171], v[66:81]
	s_add_u32 m0, s98, 0x2000
	v_lshl_add_u64 v[202:203], v[136:137], 0, s[10:11]
	global_load_lds_dwordx4 v[202:203], off
	s_waitcnt lgkmcnt(7)
	v_mfma_f32_32x32x16_bf16 v[50:65], v[156:159], v[172:175], v[50:65]
	v_mfma_f32_32x32x16_bf16 v[34:49], v[160:163], v[172:175], v[34:49]
	s_add_u32 m0, s98, 0x3000
	v_lshl_add_u64 v[202:203], v[134:135], 0, s[10:11]
	global_load_lds_dwordx4 v[202:203], off
	s_waitcnt lgkmcnt(6)
	v_mfma_f32_32x32x16_bf16 v[16:31], v[156:159], v[176:179], v[16:31]
	v_mfma_f32_32x32x16_bf16 v[0:15], v[160:163], v[176:179], v[0:15]
	s_add_u32 m0, s98, 0x4000
	v_lshl_add_u64 v[202:203], v[132:133], 0, s[10:11]
	global_load_lds_dwordx4 v[202:203], off
	s_waitcnt lgkmcnt(3)
	v_mfma_f32_32x32x16_bf16 v[114:129], v[180:183], v[188:191], v[114:129]
	v_mfma_f32_32x32x16_bf16 v[98:113], v[184:187], v[188:191], v[98:113]
	s_add_u32 m0, s98, 0x5000
	v_lshl_add_u64 v[202:203], v[130:131], 0, s[10:11]
	global_load_lds_dwordx4 v[202:203], off
	s_add_i32 s24, s21, 1
	s_cmp_lg_u32 s21, 2
	s_cselect_b32 s21, s24, 0
	s_add_u32 s10, s10, 64
	s_addc_u32 s11, s11, 0
	s_cmpk_eq_i32 s10, 0x780
	s_waitcnt lgkmcnt(2)
	v_mfma_f32_32x32x16_bf16 v[82:97], v[180:183], v[192:195], v[82:97]
	v_mfma_f32_32x32x16_bf16 v[66:81], v[184:187], v[192:195], v[66:81]
	s_waitcnt lgkmcnt(1)
	v_mfma_f32_32x32x16_bf16 v[50:65], v[180:183], v[196:199], v[50:65]
	v_mfma_f32_32x32x16_bf16 v[34:49], v[184:187], v[196:199], v[34:49]
	s_waitcnt lgkmcnt(0)
	v_mfma_f32_32x32x16_bf16 v[16:31], v[180:183], v[204:207], v[16:31]
	v_mfma_f32_32x32x16_bf16 v[0:15], v[184:187], v[204:207], v[0:15]
	s_cbranch_scc0 .LBB0_1137
	s_mul_i32 s10, s21, 0x6000
	s_waitcnt vmcnt(6)
	s_barrier
; DI u32x2 pack4(float a, float b, float c, float d) { u32x2 w; w.x = pack2(a, b); w.y = pack2(c, d); return w; }
; template <bool VT>
; DI int gemm_kloop(const bf16_t* Ag, size_t lda, const bf16_t* Bg, size_t ldb, int nk, bf16_t* ring, f32x16 (&acc)[4][2], int tid, int wm, int wn,
;                   int r, int h, int st0, bool pre, const bf16_t* AgN, const bf16_t* BgN) {
;     ...
;   asm volatile("s_waitcnt vmcnt(0)" ::: "memory");
;   __builtin_amdgcn_s_barrier();
;   if (AgN) {
;     const int s1 = st == 2 ? 0 : st + 1, s2 = s1 == 2 ? 0 : s1 + 1;
;     dma_issue(AgN, lda, BgN, ldb, 0, ring + s1 * STG, wid, lane);
;     dma_issue(AgN, lda, BgN, ldb, 1, ring + s2 * STG, wid, lane);
;   }
;   {
;     const unsigned so = (unsigned)st * (unsigned)(STG * 2);
;     g_compute_asm<VT>(oA0 + so, oA1 + so, oB0 + so, oB1 + so, acc);
;   }
;   asm volatile("s_waitcnt lgkmcnt(0)" ::: "memory");
;   return st;
;   DI void operator()(const f32x16 (&acc)[4][2], bool vt, int row0, int col0, int r, int h, const float* sR, float* stage) const {
;     const int lane = h * 32 + r, lr = lane >> 4, lc = (lane & 15) * 4;
; #pragma unroll
;     for (int mi = 0; mi < 4; ++mi) {
; #pragma unroll
;       for (int ni = 0; ni < 2; ++ni)
; #pragma unroll
;         for (int g = 0; g < 4; ++g)
;           *(f32x4*)(stage + r * 68 + ni * 32 + 8 * g + 4 * h) = (f32x4){acc[mi][ni][4 * g], acc[mi][ni][4 * g + 1], acc[mi][ni][4 * g + 2], acc[mi][ni][4 * g + 3]};
; #pragma unroll
;       for (int j = 0; j < 8; ++j) {
;         const int rr = j * 4 + lr;
;         f32x4 v = *(const f32x4*)(stage + rr * 68 + lc);
;         const size_t row = row0 + mi * 32 + rr, idx = row * DM + col0 + lc;
;         const f32x4 xin = *(const f32x4*)(rin + idx);
;         v += xin;
;         *(f32x4*)(out + idx) = v;
;         *(u32x2*)(xb + row * LDX + col0 + lc) = pack4(v.x, v.y, v.z, v.w);
;         float ss = (v.x * v.x + v.y * v.y) + (v.z * v.z + v.w * v.w);
;         ss += __shfl_xor(ss, 1); ss += __shfl_xor(ss, 2); ss += __shfl_xor(ss, 4); ss += __shfl_xor(ss, 8);
;         if ((lane & 15) == 0) ssq[row * 16 + (col0 >> 6)] = ss;
;       }
	v_add_u32_e32 v32, s10, v147
	v_add_u32_e32 v140, s10, v149
	ds_read_b128 v[132:135], v140 offset:0
	ds_read_b128 v[136:139], v140 offset:2048
	ds_read_b128 v[152:155], v32 offset:0
	ds_read_b128 v[156:159], v32 offset:2048
	ds_read_b128 v[160:163], v32 offset:4096
	ds_read_b128 v[164:167], v32 offset:6144
	v_add_u32_e32 v131, s10, v148
	v_add_u32_e32 v141, s10, v150
	ds_read_b128 v[168:171], v141 offset:0
	ds_read_b128 v[172:175], v141 offset:2048
	ds_read_b128 v[176:179], v131 offset:0
	ds_read_b128 v[180:183], v131 offset:2048
	ds_read_b128 v[184:187], v131 offset:4096
	ds_read_b128 v[188:191], v131 offset:6144
	s_waitcnt lgkmcnt(6)
	v_lshl_or_b32 v130, v151, 6, s23
	v_mfma_f32_32x32x16_bf16 v[98:113], v[136:139], v[152:155], v[98:113]
	v_mfma_f32_32x32x16_bf16 v[82:97], v[132:135], v[156:159], v[82:97]
	v_mfma_f32_32x32x16_bf16 v[66:81], v[136:139], v[156:159], v[66:81]
	v_mfma_f32_32x32x16_bf16 v[50:65], v[132:135], v[160:163], v[50:65]
	v_mfma_f32_32x32x16_bf16 v[34:49], v[136:139], v[160:163], v[34:49]
	v_mfma_f32_32x32x16_bf16 v[16:31], v[132:135], v[164:167], v[16:31]
	v_mfma_f32_32x32x16_bf16 v[0:15], v[136:139], v[164:167], v[0:15]
	v_mfma_f32_32x32x16_bf16 v[114:129], v[132:135], v[152:155], v[114:129]
	s_waitcnt lgkmcnt(0)
	s_add_i32 s10, s21, 1
	v_mfma_f32_32x32x16_bf16 v[98:113], v[172:175], v[176:179], v[98:113]
	s_cmp_lg_u32 s21, 2
	s_cselect_b32 s21, s10, 0
	s_mul_i32 s10, s21, 0x6000
	s_waitcnt vmcnt(0)
	s_barrier
	v_add_u32_e32 v32, s10, v147
	v_add_u32_e32 v131, s10, v148
	v_mfma_f32_32x32x16_bf16 v[82:97], v[168:171], v[180:183], v[82:97]
	v_add_u32_e32 v140, s10, v149
	v_add_u32_e32 v141, s10, v150
	ds_read_b128 v[132:135], v140 offset:0
	ds_read_b128 v[136:139], v140 offset:2048
	ds_read_b128 v[148:151], v32 offset:0
	ds_read_b128 v[152:155], v32 offset:2048
	ds_read_b128 v[156:159], v32 offset:4096
	v_mfma_f32_32x32x16_bf16 v[66:81], v[172:175], v[180:183], v[66:81]
	ds_read_b128 v[160:163], v32 offset:6144
	ds_read_b128 v[164:167], v141 offset:0
	v_mfma_f32_32x32x16_bf16 v[50:65], v[168:171], v[184:187], v[50:65]
	v_mfma_f32_32x32x16_bf16 v[34:49], v[172:175], v[184:187], v[34:49]
	v_mfma_f32_32x32x16_bf16 v[16:31], v[168:171], v[188:191], v[16:31]
	v_mfma_f32_32x32x16_bf16 v[0:15], v[172:175], v[188:191], v[0:15]
	v_mfma_f32_32x32x16_bf16 v[114:129], v[168:171], v[176:179], v[114:129]
	ds_read_b128 v[168:171], v141 offset:2048
	ds_read_b128 v[172:175], v131 offset:0
	ds_read_b128 v[176:179], v131 offset:2048
	ds_read_b128 v[180:183], v131 offset:4096
	ds_read_b128 v[184:187], v131 offset:6144
	s_waitcnt lgkmcnt(6)
	s_nop 0
	v_mfma_f32_32x32x16_bf16 v[98:113], v[136:139], v[148:151], v[98:113]
	v_mfma_f32_32x32x16_bf16 v[82:97], v[132:135], v[152:155], v[82:97]
	v_mfma_f32_32x32x16_bf16 v[66:81], v[136:139], v[152:155], v[66:81]
	v_mfma_f32_32x32x16_bf16 v[50:65], v[132:135], v[156:159], v[50:65]
	v_mfma_f32_32x32x16_bf16 v[34:49], v[136:139], v[156:159], v[34:49]
	v_mfma_f32_32x32x16_bf16 v[16:31], v[132:135], v[160:163], v[16:31]
	v_mfma_f32_32x32x16_bf16 v[0:15], v[136:139], v[160:163], v[0:15]
	v_mfma_f32_32x32x16_bf16 v[114:129], v[132:135], v[148:151], v[114:129]
	s_waitcnt lgkmcnt(0)
	v_mul_lo_u32 v32, v145, s68
	v_mfma_f32_32x32x16_bf16 v[114:129], v[164:167], v[172:175], v[114:129]
	v_and_b32_e32 v131, 0xffffff80, v144
	v_add_u32_e32 v134, s22, v131
	v_mad_u32_u24 v131, v146, s69, v32
	v_lshlrev_b32_e32 v132, 4, v143
	v_add_u32_e32 v135, v131, v132
	s_waitcnt lgkmcnt(0)
	s_waitcnt vmcnt(0) lgkmcnt(0)
	v_mfma_f32_32x32x16_bf16 v[98:113], v[168:171], v[172:175], v[98:113]
	s_barrier
	v_and_b32_e32 v137, 15, v144
	s_nop 2
	ds_write_b128 v135, v[114:117]
	ds_write_b128 v135, v[118:121] offset:32
	ds_write_b128 v135, v[122:125] offset:64
	ds_write_b128 v135, v[126:129] offset:96
	s_nop 2
	ds_write_b128 v135, v[98:101] offset:128
	ds_write_b128 v135, v[102:105] offset:160
	ds_write_b128 v135, v[106:109] offset:192
	v_or_b32_e32 v100, v134, v142
	v_lshlrev_b32_e32 v136, 2, v137
	v_ashrrev_i32_e32 v131, 31, v130
	v_ashrrev_i32_e32 v101, 31, v100
	v_or_b32_e32 v132, v130, v136
	v_mov_b32_e32 v133, v131
	v_lshlrev_b64 v[98:99], 10, v[100:101]
	v_lshl_add_u64 v[98:99], v[98:99], 0, v[132:133]
	v_lshlrev_b64 v[116:117], 2, v[98:99]
	ds_write_b128 v135, v[110:113] offset:224
	v_lshl_add_u64 v[98:99], s[6:7], 0, v[116:117]
	flat_load_dwordx4 v[108:111], v[98:99]
	v_and_b32_e32 v99, 64, v208
	v_xor_b32_e32 v98, 1, v208
	v_lshl_or_b32 v106, v137, 4, v32
	v_add_u32_e32 v32, 64, v99
	v_xor_b32_e32 v102, 2, v208
	v_cmp_lt_i32_e32 vcc, v98, v32
	v_xor_b32_e32 v103, 4, v208
	v_xor_b32_e32 v105, 8, v208
	v_cndmask_b32_e32 v98, v208, v98, vcc
	v_cmp_lt_i32_e32 vcc, v102, v32
	v_lshlrev_b32_e32 v104, 2, v98
	v_mfma_f32_32x32x16_bf16 v[82:97], v[164:167], v[176:179], v[82:97]
	v_cndmask_b32_e32 v99, v208, v102, vcc
	v_mad_u32_u24 v102, v142, s69, v106
	ds_read_b128 v[112:115], v102
	v_cmp_lt_i32_e32 vcc, v103, v32
	s_waitcnt vmcnt(0) lgkmcnt(0)
	v_pk_add_f32 v[110:111], v[114:115], v[110:111]
	v_pk_add_f32 v[108:109], v[112:113], v[108:109]
	v_cndmask_b32_e32 v102, v208, v103, vcc
	v_lshlrev_b32_e32 v103, 2, v99
	v_mul_f32_e32 v98, v109, v109
	v_mul_f32_e32 v99, v111, v111
	v_fmac_f32_e32 v98, v108, v108
	v_fmac_f32_e32 v99, v110, v110
	v_add_f32_e32 v99, v98, v99
	ds_bpermute_b32 v107, v104, v99
	v_cmp_lt_i32_e32 vcc, v105, v32
	v_lshlrev_b32_e32 v102, 2, v102
	v_mfma_f32_32x32x16_bf16 v[66:81], v[168:171], v[176:179], v[66:81]
	v_cndmask_b32_e32 v32, v208, v105, vcc
	v_lshlrev_b32_e32 v105, 2, v32
	s_waitcnt lgkmcnt(0)
	v_add_f32_e32 v32, v99, v107
	ds_bpermute_b32 v107, v103, v32
	v_lshl_add_u64 v[112:113], s[0:1], 0, v[116:117]
	flat_store_dwordx4 v[112:113], v[108:111]
	v_cvt_pk_bf16_f32 v112, v108, v109
	v_mfma_f32_32x32x16_bf16 v[50:65], v[164:167], v[180:183], v[50:65]
	s_waitcnt lgkmcnt(0)
	v_add_f32_e32 v32, v32, v107
	ds_bpermute_b32 v107, v102, v32
	v_mov_b64_e32 v[108:109], s[2:3]
	v_cvt_pk_bf16_f32 v113, v110, v111
	v_mad_i64_i32 v[110:111], s[10:11], v100, s74, v[108:109]
	s_waitcnt lgkmcnt(0)
	v_add_f32_e32 v107, v32, v107
	v_mfma_f32_32x32x16_bf16 v[34:49], v[168:171], v[180:183], v[34:49]
	ds_bpermute_b32 v108, v105, v107
	v_ashrrev_i32_e32 v98, 6, v130
	v_lshl_add_u64 v[110:111], v[130:131], 1, v[110:111]
	v_lshlrev_b32_e32 v32, 3, v137
	v_cmp_eq_u32_e32 vcc, 0, v137
	v_ashrrev_i32_e32 v99, 31, v98
	v_lshl_add_u64 v[110:111], v[110:111], 0, v[32:33]
	v_mfma_f32_32x32x16_bf16 v[16:31], v[164:167], v[184:187], v[16:31]
	flat_store_dwordx2 v[110:111], v[112:113]
	v_mfma_f32_32x32x16_bf16 v[0:15], v[168:171], v[184:187], v[0:15]
	s_and_saveexec_b64 s[10:11], vcc
	s_cbranch_execz .LBB0_1140
	v_lshlrev_b64 v[100:101], 6, v[100:101]
	v_lshl_add_u64 v[100:101], s[4:5], 0, v[100:101]
	v_lshl_add_u64 v[100:101], v[98:99], 2, v[100:101]
	s_waitcnt lgkmcnt(0)
	v_add_f32_e32 v32, v107, v108
	flat_store_dword v[100:101], v32

; template <bool VT>
; DI int gemm_kloop(const bf16_t* Ag, size_t lda, const bf16_t* Bg, size_t ldb, int nk, bf16_t* ring, f32x16 (&acc)[4][2], int tid, int wm, int wn,
;                   int r, int h, int st0, bool pre, const bf16_t* AgN, const bf16_t* BgN) {
;   const int wid = tid >> 6, lane = tid & 63;
;   const unsigned base = (unsigned)(unsigned long long)ring;
;   const int q = (r >> 2) & 3;
;   const unsigned rA = base + (unsigned)(wm * 128 + r) * 64u, rB = base + (unsigned)STG_A * 2u + (unsigned)(wn * 64 + r) * 64u;
;   const unsigned oA0 = rA + (unsigned)((h ^ q) & 3) * 16u, oA1 = rA + (unsigned)(((2 + h) ^ q) & 3) * 16u;
;   const unsigned oB0 = rB + (unsigned)((h ^ q) & 3) * 16u, oB1 = rB + (unsigned)(((2 + h) ^ q) & 3) * 16u;
;   int st = st0;
;   if (!pre) {
;     dma_issue(Ag, lda, Bg, ldb, 0, ring + st * STG, wid, lane);
;     dma_issue(Ag, lda, Bg, ldb, 1, ring + (st == 2 ? 0 : st + 1) * STG, wid, lane);
;   }
;     ...
;   f32x16 acc[4][2];
; #pragma unroll
;   for (int a = 0; a < 4; ++a)
; #pragma unroll
;     for (int b = 0; b < 2; ++b)
; #pragma unroll
;       for (int i = 0; i < 16; ++i) acc[a][b][i] = 0.f;
.LBB0_1314:
	s_ashr_i32 s9, s18, 31
	s_ashr_i32 s8, s18, 3
	s_lshr_b32 s9, s9, 26
	s_add_i32 s9, s8, s9
	s_ashr_i32 s27, s9, 6
	s_andn2_b32 s9, s9, 63
	s_sub_i32 s8, s8, s9
	s_and_b32 s9, s18, 7
	s_add_i32 s9, s27, s9
	v_mov_b32_e32 v143, v242
	s_lshl_b32 s20, s8, 8
	s_lshl_b32 s8, s8, 4
	s_lshl_b32 s9, s9, 11
	v_ashrrev_i32_e32 v145, 6, v143
	s_and_b32 s28, s20, 0x700
	s_and_b32 s21, s8, 0xffffff80
	v_bfe_u32 v144, v143, 5, 1
	s_or_b32 s20, s9, s28
	s_mul_i32 s8, s21, 0xb40
	s_waitcnt vmcnt(0)
	v_and_b32_e32 v146, 31, v143
	v_and_b32_e32 v151, 1, v145
	v_lshrrev_b32_e32 v0, 2, v143
	s_and_b32 s26, s17, 7
	s_ashr_i32 s9, s8, 31
	s_mul_i32 s22, s20, 0x1680
	v_lshlrev_b32_e32 v2, 6, v143
	v_lshlrev_b32_e32 v3, 6, v146
	v_lshlrev_b32_e32 v4, 12, v151
	v_bitop3_b32 v0, v0, v144, 3 bitop3:0x6c
	s_mul_hi_i32 s23, s20, 0x1680
	s_add_u32 s22, s10, s22
	v_bfe_u32 v1, v143, 2, 2
	v_and_or_b32 v2, v2, s93, v3
	v_or3_b32 v3, v3, v4, s94
	v_lshlrev_b32_e32 v0, 4, v0
	v_bfe_u32 v142, v143, 4, 2
	s_addc_u32 s23, s11, s23
	s_lshl_b64 s[8:9], s[8:9], 1
	v_or_b32_e32 v147, v0, v2
	v_bitop3_b32 v1, v144, v1, 2 bitop3:0x36
	v_or_b32_e32 v149, v3, v0
	v_bitop3_b32 v0, v142, v143, 3 bitop3:0x78
	s_add_u32 s24, s12, s8
	v_lshlrev_b32_e32 v1, 4, v1
	s_mul_i32 s29, s19, 0x3000
	v_bfe_u32 v8, v143, 2, 4
	v_lshlrev_b32_e32 v32, 4, v0
	s_addc_u32 s25, s13, s9
	v_or_b32_e32 v148, v1, v2
	v_or_b32_e32 v150, v1, v3
	s_lshl_b32 s30, s29, 1
	v_lshl_add_u64 v[0:1], s[22:23], 0, v[32:33]
	v_lshl_or_b32 v12, v145, 4, v8
	s_movk_i32 s31, 0x1680
	v_lshlrev_b32_e32 v13, 10, v145
	v_mad_i64_i32 v[2:3], s[22:23], v12, s31, v[0:1]
	v_add_u32_e32 v14, s30, v13
	v_add_u32_e32 v6, 4, v145
	v_readfirstlane_b32 s22, v14
	v_lshl_or_b32 v15, v6, 4, v8
	v_lshlrev_b32_e32 v16, 10, v6
	s_mov_b32 m0, s22
	v_mad_i64_i32 v[4:5], s[22:23], v15, s31, v[0:1]
	v_add_u32_e32 v17, s30, v16
	v_add_u32_e32 v9, 8, v145
	v_lshlrev_b32_e32 v153, 9, v6
	v_readfirstlane_b32 s22, v17
	v_lshl_or_b32 v6, v9, 4, v8
	v_lshlrev_b32_e32 v154, 10, v9
	s_waitcnt lgkmcnt(0)
	s_barrier
	global_load_lds_dwordx4 v[2:3], off
	s_mov_b32 m0, s22
	v_mad_i64_i32 v[6:7], s[22:23], v6, s31, v[0:1]
	v_add_u32_e32 v9, s30, v154
	global_load_lds_dwordx4 v[4:5], off
	v_readfirstlane_b32 s22, v9
	v_add_u32_e32 v9, 12, v145
	v_lshl_or_b32 v8, v9, 4, v8
	v_lshlrev_b32_e32 v155, 10, v9
	s_mov_b32 m0, s22
	v_mad_i64_i32 v[0:1], s[22:23], v8, s31, v[0:1]
	v_add_u32_e32 v8, s30, v155
	global_load_lds_dwordx4 v[6:7], off
	v_readfirstlane_b32 s22, v8
	v_lshl_add_u64 v[8:9], s[24:25], 0, v[32:33]
	s_mov_b32 m0, s22
	v_mad_i64_i32 v[10:11], s[22:23], v12, s31, v[8:9]
	v_add_u32_e32 v14, 0x4000, v14
	global_load_lds_dwordx4 v[0:1], off
	v_readfirstlane_b32 s22, v14
	s_mov_b32 m0, s22
	v_mad_i64_i32 v[8:9], s[22:23], v15, s31, v[8:9]
	v_add_u32_e32 v14, 0x4000, v17
	s_addk_i32 s29, 0x3000
	v_readfirstlane_b32 s22, v14
	s_cmp_lg_u32 s19, 2
	global_load_lds_dwordx4 v[10:11], off
	s_mov_b32 m0, s22
	s_cselect_b32 s22, s29, 0
	s_lshl_b32 s22, s22, 1
	v_add_u32_e32 v13, s22, v13
	global_load_lds_dwordx4 v[8:9], off
	v_readfirstlane_b32 s23, v13
	v_lshl_add_u64 v[2:3], v[2:3], 0, 64
	s_mov_b32 m0, s23
	v_lshl_add_u64 v[0:1], v[0:1], 0, 64
	global_load_lds_dwordx4 v[2:3], off
	v_lshl_add_u64 v[2:3], v[4:5], 0, 64
	v_add_u32_e32 v4, s22, v16
	v_add_u32_e32 v5, s22, v154
	v_readfirstlane_b32 s23, v4
	s_mov_b32 m0, s23
	v_readfirstlane_b32 s23, v5
	global_load_lds_dwordx4 v[2:3], off
	v_lshl_add_u64 v[2:3], v[6:7], 0, 64
	s_mov_b32 m0, s23
	s_add_u32 s8, s15, s8
	global_load_lds_dwordx4 v[2:3], off
	v_add_u32_e32 v2, s22, v155
	s_addc_u32 s9, s16, s9
	v_readfirstlane_b32 s22, v2
	v_add_u32_e32 v2, 0x4000, v13
	s_mov_b32 m0, s22
	v_readfirstlane_b32 s22, v2
	v_add_u32_e32 v2, 0x4000, v4
	global_load_lds_dwordx4 v[0:1], off
	v_lshl_add_u64 v[0:1], v[10:11], 0, 64
	s_mov_b32 m0, s22
	v_readfirstlane_b32 s22, v2
	global_load_lds_dwordx4 v[0:1], off
	v_lshl_add_u64 v[0:1], v[8:9], 0, 64
	s_mov_b32 m0, s22
	v_mad_i64_i32 v[2:3], s[22:23], v12, s31, 0
	global_load_lds_dwordx4 v[0:1], off
	v_add_u32_e32 v0, 64, v12
	v_mad_i64_i32 v[0:1], s[22:23], v0, s31, 0
	v_or_b32_e32 v0, v0, v32
	v_or_b32_e32 v2, v2, v32
	s_add_i32 s27, s27, s26
	v_lshl_add_u64 v[130:131], s[8:9], 0, v[0:1]
	v_lshl_add_u64 v[132:133], s[8:9], 0, v[2:3]
	s_lshl_b32 s8, s27, 11
	s_or_b32 s22, s8, s28
	s_mul_hi_i32 s9, s22, 0x1680
	s_mul_i32 s8, s22, 0x1680
	v_add_u32_e32 v6, 0xc0, v12
	v_mov_b64_e32 v[4:5], s[8:9]
	v_mad_i64_i32 v[6:7], s[8:9], v6, s31, v[4:5]
	v_or_b32_e32 v6, v6, v32
	v_lshl_add_u64 v[134:135], s[6:7], 0, v[6:7]
	v_add_u32_e32 v6, 0x80, v12
	v_mad_i64_i32 v[4:5], s[8:9], v6, s31, v[4:5]
	v_or_b32_e32 v4, v4, v32
	v_lshl_add_u64 v[136:137], s[6:7], 0, v[4:5]
	v_mov_b32_e32 v4, 0x1680
	v_mad_i64_i32 v[0:1], s[8:9], s22, v4, v[0:1]
	v_lshl_add_u64 v[138:139], s[6:7], 0, v[0:1]
	v_mad_i64_i32 v[0:1], s[8:9], s22, v4, v[2:3]
	v_lshl_add_u64 v[140:141], s[6:7], 0, v[0:1]
	v_mov_b32_e32 v0, 0
	v_lshlrev_b32_e32 v152, 9, v145
	s_mov_b64 s[8:9], 0
	v_mov_b32_e32 v1, v0
	v_mov_b32_e32 v2, v0
	v_mov_b32_e32 v3, v0
	v_mov_b32_e32 v4, v0
	v_mov_b32_e32 v5, v0
	v_mov_b32_e32 v6, v0
	v_mov_b32_e32 v7, v0
	v_mov_b32_e32 v8, v0
	v_mov_b32_e32 v9, v0
	v_mov_b32_e32 v10, v0
	v_mov_b32_e32 v11, v0
	v_mov_b32_e32 v12, v0
	v_mov_b32_e32 v13, v0
	v_mov_b32_e32 v14, v0
	v_mov_b32_e32 v15, v0
	v_mov_b32_e32 v16, v0
	v_mov_b32_e32 v17, v0
	v_mov_b32_e32 v18, v0
	v_mov_b32_e32 v19, v0
	v_mov_b32_e32 v20, v0
	v_mov_b32_e32 v21, v0
	v_mov_b32_e32 v22, v0
	v_mov_b32_e32 v23, v0
	v_mov_b32_e32 v24, v0
	v_mov_b32_e32 v25, v0
	v_mov_b32_e32 v26, v0
	v_mov_b32_e32 v27, v0
	v_mov_b32_e32 v28, v0
; #define MFMA(a, b, c) __builtin_amdgcn_mfma_f32_32x32x16_bf16((a), (b), (c), 0, 0, 0)
; #define DSR(dst, addr, off) asm volatile("ds_read_b128 %0, %1 offset:" #off : "=&v"(dst) : "v"(addr))
; DI void dma_issue(const bf16_t* Ag, size_t lda, const bf16_t* Bg, size_t ldb, int kt, bf16_t* stage, int wid, int lane) {
;   const int rl = lane >> 2, c = (lane & 3) ^ ((lane >> 4) & 3);
; #pragma unroll
;   for (int i = 0; i < 4; ++i) {
;     const int j = wid + 4 * i;
;     __builtin_amdgcn_global_load_lds((const unsigned*)(Ag + (size_t)(16 * j + rl) * lda + kt * 32 + c * 8), (unsigned*)(stage + j * 512), 16, 0, 0);
;   }
; #pragma unroll
;   for (int i = 0; i < 2; ++i) {
;     const int j = wid + 4 * i;
;     __builtin_amdgcn_global_load_lds((const unsigned*)(Bg + (size_t)(16 * j + rl) * ldb + kt * 32 + c * 8), (unsigned*)(stage + STG_A + j * 512), 16, 0, 0);
;   }
; }
; template <bool VT>
; DI void g_compute_asm(unsigned aA0, unsigned aA1, unsigned aB0, unsigned aB1, f32x16 (&acc)[4][2]) {
;   bf16x8 a0[4], a1[4], b0[2], b1[2];
;   DSR(b0[0], aB0, 0); DSR(b0[1], aB0, 2048);
;   DSR(a0[0], aA0, 0); DSR(a0[1], aA0, 2048); DSR(a0[2], aA0, 4096); DSR(a0[3], aA0, 6144);
;   DSR(b1[0], aB1, 0); DSR(b1[1], aB1, 2048);
;   DSR(a1[0], aA1, 0); DSR(a1[1], aA1, 2048); DSR(a1[2], aA1, 4096); DSR(a1[3], aA1, 6144);
;   asm volatile("s_waitcnt lgkmcnt(6)" : "+v"(b0[0]), "+v"(b0[1]), "+v"(a0[0]), "+v"(a0[1]), "+v"(a0[2]), "+v"(a0[3]));
; #pragma unroll
;   for (int mi = 0; mi < 4; ++mi)
; #pragma unroll
;     for (int ni = 0; ni < 2; ++ni) {
;       if (VT) acc[mi][ni] = MFMA(a0[mi], b0[ni], acc[mi][ni]);
;       else acc[mi][ni] = MFMA(b0[ni], a0[mi], acc[mi][ni]);
;     }
;   __builtin_amdgcn_sched_barrier(0);
;   asm volatile("s_waitcnt lgkmcnt(0)" : "+v"(b1[0]), "+v"(b1[1]), "+v"(a1[0]), "+v"(a1[1]), "+v"(a1[2]), "+v"(a1[3]));
; #pragma unroll
;   for (int mi = 0; mi < 4; ++mi)
; #pragma unroll
;     for (int ni = 0; ni < 2; ++ni) {
;       if (VT) acc[mi][ni] = MFMA(a1[mi], b1[ni], acc[mi][ni]);
;       else acc[mi][ni] = MFMA(b1[ni], a1[mi], acc[mi][ni]);
;     }
; }
	v_mov_b32_e32 v29, v0
	v_mov_b32_e32 v30, v0
	v_mov_b32_e32 v31, v0
	v_mov_b32_e32 v34, v0
	v_mov_b32_e32 v35, v0
	v_mov_b32_e32 v36, v0
	v_mov_b32_e32 v37, v0
	v_mov_b32_e32 v38, v0
	v_mov_b32_e32 v39, v0
	v_mov_b32_e32 v40, v0
	v_mov_b32_e32 v41, v0
	v_mov_b32_e32 v42, v0
	v_mov_b32_e32 v43, v0
	v_mov_b32_e32 v44, v0
	v_mov_b32_e32 v45, v0
	v_mov_b32_e32 v46, v0
	v_mov_b32_e32 v47, v0
	v_mov_b32_e32 v48, v0
	v_mov_b32_e32 v49, v0
	v_mov_b32_e32 v50, v0
	v_mov_b32_e32 v51, v0
	v_mov_b32_e32 v52, v0
	v_mov_b32_e32 v53, v0
	v_mov_b32_e32 v54, v0
	v_mov_b32_e32 v55, v0
	v_mov_b32_e32 v56, v0
	v_mov_b32_e32 v57, v0
	v_mov_b32_e32 v58, v0
	v_mov_b32_e32 v59, v0
	v_mov_b32_e32 v60, v0
	v_mov_b32_e32 v61, v0
	v_mov_b32_e32 v62, v0
	v_mov_b32_e32 v63, v0
	v_mov_b32_e32 v64, v0
	v_mov_b32_e32 v65, v0
	v_mov_b32_e32 v66, v0
	v_mov_b32_e32 v67, v0
	v_mov_b32_e32 v68, v0
	v_mov_b32_e32 v69, v0
	v_mov_b32_e32 v70, v0
	v_mov_b32_e32 v71, v0
	v_mov_b32_e32 v72, v0
	v_mov_b32_e32 v73, v0
	v_mov_b32_e32 v74, v0
	v_mov_b32_e32 v75, v0
	v_mov_b32_e32 v76, v0
	v_mov_b32_e32 v77, v0
	v_mov_b32_e32 v78, v0
	v_mov_b32_e32 v79, v0
	v_mov_b32_e32 v80, v0
	v_mov_b32_e32 v81, v0
	v_mov_b32_e32 v82, v0
	v_mov_b32_e32 v83, v0
	v_mov_b32_e32 v84, v0
	v_mov_b32_e32 v85, v0
	v_mov_b32_e32 v86, v0
	v_mov_b32_e32 v87, v0
	v_mov_b32_e32 v88, v0
	v_mov_b32_e32 v89, v0
	v_mov_b32_e32 v90, v0
	v_mov_b32_e32 v91, v0
	v_mov_b32_e32 v92, v0
	v_mov_b32_e32 v93, v0
	v_mov_b32_e32 v94, v0
	v_mov_b32_e32 v95, v0
	v_mov_b32_e32 v96, v0
	v_mov_b32_e32 v97, v0
	v_mov_b32_e32 v98, v0
	v_mov_b32_e32 v99, v0
	v_mov_b32_e32 v100, v0
	v_mov_b32_e32 v101, v0
	v_mov_b32_e32 v102, v0
	v_mov_b32_e32 v103, v0
	v_mov_b32_e32 v104, v0
	v_mov_b32_e32 v105, v0
	v_mov_b32_e32 v106, v0
	v_mov_b32_e32 v107, v0
	v_mov_b32_e32 v108, v0
	v_mov_b32_e32 v109, v0
	v_mov_b32_e32 v110, v0
	v_mov_b32_e32 v111, v0
	v_mov_b32_e32 v112, v0
	v_mov_b32_e32 v113, v0
	v_mov_b32_e32 v114, v0
	v_mov_b32_e32 v115, v0
	v_mov_b32_e32 v116, v0
	v_mov_b32_e32 v117, v0
	v_mov_b32_e32 v118, v0
	v_mov_b32_e32 v119, v0
	v_mov_b32_e32 v120, v0
	v_mov_b32_e32 v121, v0
	v_mov_b32_e32 v122, v0
	v_mov_b32_e32 v123, v0
	v_mov_b32_e32 v124, v0
	v_mov_b32_e32 v125, v0
	v_mov_b32_e32 v126, v0
	v_mov_b32_e32 v127, v0
	v_mov_b32_e32 v128, v0
	v_mov_b32_e32 v129, v0
	v_readfirstlane_b32 s99, v152
	s_lshl_b32 s99, s99, 1
.LBB0_1315:
	s_mul_i32 s22, s19, 0x3000
	v_lshl_add_u64 v[156:157], v[140:141], 0, s[8:9]
	s_mul_i32 s98, s19, 0x3000
	s_addk_i32 s98, 0xd000
	s_cmp_lg_u32 s19, 0
	s_cselect_b32 s98, s98, 0x6000
	s_lshl_b32 s98, s98, 1
	s_add_u32 s98, s98, s99
	s_mul_i32 s22, s19, 0x6000
	v_add_u32_e32 v164, s22, v149
	v_add_u32_e32 v32, s22, v147
	v_add_u32_e32 v188, s22, v150
	v_add_u32_e32 v204, s22, v148
	s_mov_b32 m0, s98
	s_waitcnt vmcnt(6)
	s_barrier
	global_load_lds_dwordx4 v[156:157], off
	ds_read_b128 v[156:159], v164 offset:0
	ds_read_b128 v[160:163], v164 offset:2048
	ds_read_b128 v[164:167], v32 offset:0
	ds_read_b128 v[168:171], v32 offset:2048
	ds_read_b128 v[172:175], v32 offset:4096
	ds_read_b128 v[176:179], v32 offset:6144
	ds_read_b128 v[180:183], v188 offset:0
	ds_read_b128 v[184:187], v188 offset:2048
	ds_read_b128 v[188:191], v204 offset:0
	ds_read_b128 v[192:195], v204 offset:2048
	ds_read_b128 v[196:199], v204 offset:4096
	ds_read_b128 v[200:203], v204 offset:6144
	s_waitcnt lgkmcnt(9)
	v_mfma_f32_32x32x16_bf16 v[114:129], v[156:159], v[164:167], v[114:129]
	v_mfma_f32_32x32x16_bf16 v[98:113], v[160:163], v[164:167], v[98:113]
	s_add_u32 m0, s98, 0x1000
	v_lshl_add_u64 v[206:207], v[138:139], 0, s[8:9]
	global_load_lds_dwordx4 v[206:207], off
	s_waitcnt lgkmcnt(8)
	v_mfma_f32_32x32x16_bf16 v[82:97], v[156:159], v[168:171], v[82:97]
	v_mfma_f32_32x32x16_bf16 v[66:81], v[160:163], v[168:171], v[66:81]
	s_add_u32 m0, s98, 0x2000
	v_lshl_add_u64 v[206:207], v[136:137], 0, s[8:9]
	global_load_lds_dwordx4 v[206:207], off
	s_waitcnt lgkmcnt(7)
	v_mfma_f32_32x32x16_bf16 v[50:65], v[156:159], v[172:175], v[50:65]
	v_mfma_f32_32x32x16_bf16 v[34:49], v[160:163], v[172:175], v[34:49]
	s_add_u32 m0, s98, 0x3000
	v_lshl_add_u64 v[206:207], v[134:135], 0, s[8:9]
	global_load_lds_dwordx4 v[206:207], off
	s_waitcnt lgkmcnt(6)
	v_mfma_f32_32x32x16_bf16 v[16:31], v[156:159], v[176:179], v[16:31]
	v_mfma_f32_32x32x16_bf16 v[0:15], v[160:163], v[176:179], v[0:15]
	s_add_u32 m0, s98, 0x4000
	v_lshl_add_u64 v[206:207], v[132:133], 0, s[8:9]
	global_load_lds_dwordx4 v[206:207], off
	s_waitcnt lgkmcnt(3)
	v_mfma_f32_32x32x16_bf16 v[114:129], v[180:183], v[188:191], v[114:129]
	v_mfma_f32_32x32x16_bf16 v[98:113], v[184:187], v[188:191], v[98:113]
	s_add_u32 m0, s98, 0x5000
	v_lshl_add_u64 v[206:207], v[130:131], 0, s[8:9]
	global_load_lds_dwordx4 v[206:207], off
	s_add_i32 s22, s19, 1
	s_cmp_lg_u32 s19, 2
	s_cselect_b32 s19, s22, 0
	s_add_u32 s8, s8, 64
	s_addc_u32 s9, s9, 0
	s_cmpk_eq_i32 s8, 0x1580
	s_waitcnt lgkmcnt(2)
	v_mfma_f32_32x32x16_bf16 v[82:97], v[180:183], v[192:195], v[82:97]
	v_mfma_f32_32x32x16_bf16 v[66:81], v[184:187], v[192:195], v[66:81]
	s_waitcnt lgkmcnt(1)
	v_mfma_f32_32x32x16_bf16 v[50:65], v[180:183], v[196:199], v[50:65]
	v_mfma_f32_32x32x16_bf16 v[34:49], v[184:187], v[196:199], v[34:49]
	s_waitcnt lgkmcnt(0)
	v_mfma_f32_32x32x16_bf16 v[16:31], v[180:183], v[200:203], v[16:31]
	v_mfma_f32_32x32x16_bf16 v[0:15], v[184:187], v[200:203], v[0:15]
	s_cbranch_scc0 .LBB0_1315
	s_mul_i32 s8, s19, 0x6000
	s_waitcnt vmcnt(6)
	s_barrier
; DI u32x2 pack4(float a, float b, float c, float d) { u32x2 w; w.x = pack2(a, b); w.y = pack2(c, d); return w; }
; template <bool VT>
; DI int gemm_kloop(const bf16_t* Ag, size_t lda, const bf16_t* Bg, size_t ldb, int nk, bf16_t* ring, f32x16 (&acc)[4][2], int tid, int wm, int wn,
;                   int r, int h, int st0, bool pre, const bf16_t* AgN, const bf16_t* BgN) {
;     ...
;   asm volatile("s_waitcnt vmcnt(0)" ::: "memory");
;   __builtin_amdgcn_s_barrier();
;   if (AgN) {
;     const int s1 = st == 2 ? 0 : st + 1, s2 = s1 == 2 ? 0 : s1 + 1;
;     dma_issue(AgN, lda, BgN, ldb, 0, ring + s1 * STG, wid, lane);
;     dma_issue(AgN, lda, BgN, ldb, 1, ring + s2 * STG, wid, lane);
;   }
;   {
;     const unsigned so = (unsigned)st * (unsigned)(STG * 2);
;     g_compute_asm<VT>(oA0 + so, oA1 + so, oB0 + so, oB1 + so, acc);
;   }
;   asm volatile("s_waitcnt lgkmcnt(0)" ::: "memory");
;   return st;
;   DI void operator()(const f32x16 (&acc)[4][2], bool vt, int row0, int col0, int r, int h, const float* sR, float* stage) const {
;     const int lane = h * 32 + r, lr = lane >> 4, lc = (lane & 15) * 4;
; #pragma unroll
;     for (int mi = 0; mi < 4; ++mi) {
; #pragma unroll
;       for (int ni = 0; ni < 2; ++ni)
; #pragma unroll
;         for (int g = 0; g < 4; ++g)
;           *(f32x4*)(stage + r * 68 + ni * 32 + 8 * g + 4 * h) = (f32x4){acc[mi][ni][4 * g], acc[mi][ni][4 * g + 1], acc[mi][ni][4 * g + 2], acc[mi][ni][4 * g + 3]};
; #pragma unroll
;       for (int j = 0; j < 8; ++j) {
;         const int rr = j * 4 + lr;
;         f32x4 v = *(const f32x4*)(stage + rr * 68 + lc);
;         const size_t row = row0 + mi * 32 + rr, idx = row * DM + col0 + lc;
;         const f32x4 xin = *(const f32x4*)(rin + idx);
;         v += xin;
;         *(f32x4*)(out + idx) = v;
;         *(u32x2*)(xb + row * LDX + col0 + lc) = pack4(v.x, v.y, v.z, v.w);
;         float ss = (v.x * v.x + v.y * v.y) + (v.z * v.z + v.w * v.w);
;         ss += __shfl_xor(ss, 1); ss += __shfl_xor(ss, 2); ss += __shfl_xor(ss, 4); ss += __shfl_xor(ss, 8);
;         if ((lane & 15) == 0) ssq[row * 16 + (col0 >> 6)] = ss;
;       }
	v_add_u32_e32 v32, s8, v147
	v_add_u32_e32 v140, s8, v149
	ds_read_b128 v[132:135], v140 offset:0
	ds_read_b128 v[136:139], v140 offset:2048
	ds_read_b128 v[152:155], v32 offset:0
	ds_read_b128 v[156:159], v32 offset:2048
	ds_read_b128 v[160:163], v32 offset:4096
	ds_read_b128 v[164:167], v32 offset:6144
	v_add_u32_e32 v131, s8, v148
	v_add_u32_e32 v141, s8, v150
	ds_read_b128 v[168:171], v141 offset:0
	ds_read_b128 v[172:175], v141 offset:2048
	ds_read_b128 v[176:179], v131 offset:0
	ds_read_b128 v[180:183], v131 offset:2048
	ds_read_b128 v[184:187], v131 offset:4096
	ds_read_b128 v[188:191], v131 offset:6144
	s_waitcnt lgkmcnt(6)
	v_lshl_or_b32 v130, v151, 6, s21
	v_mfma_f32_32x32x16_bf16 v[98:113], v[136:139], v[152:155], v[98:113]
	v_mfma_f32_32x32x16_bf16 v[82:97], v[132:135], v[156:159], v[82:97]
	v_mfma_f32_32x32x16_bf16 v[66:81], v[136:139], v[156:159], v[66:81]
	v_mfma_f32_32x32x16_bf16 v[50:65], v[132:135], v[160:163], v[50:65]
	v_mfma_f32_32x32x16_bf16 v[34:49], v[136:139], v[160:163], v[34:49]
	v_mfma_f32_32x32x16_bf16 v[16:31], v[132:135], v[164:167], v[16:31]
	v_mfma_f32_32x32x16_bf16 v[0:15], v[136:139], v[164:167], v[0:15]
	v_mfma_f32_32x32x16_bf16 v[114:129], v[132:135], v[152:155], v[114:129]
	s_waitcnt lgkmcnt(0)
	s_add_i32 s8, s19, 1
	v_mfma_f32_32x32x16_bf16 v[98:113], v[172:175], v[176:179], v[98:113]
	s_cmp_lg_u32 s19, 2
	s_cselect_b32 s19, s8, 0
	s_mul_i32 s8, s19, 0x6000
	s_waitcnt vmcnt(0)
	s_barrier
	v_add_u32_e32 v32, s8, v147
	v_add_u32_e32 v131, s8, v148
	v_mfma_f32_32x32x16_bf16 v[82:97], v[168:171], v[180:183], v[82:97]
	v_add_u32_e32 v140, s8, v149
	v_add_u32_e32 v141, s8, v150
	ds_read_b128 v[132:135], v140 offset:0
	ds_read_b128 v[136:139], v140 offset:2048
	ds_read_b128 v[148:151], v32 offset:0
	ds_read_b128 v[152:155], v32 offset:2048
	ds_read_b128 v[156:159], v32 offset:4096
	v_mfma_f32_32x32x16_bf16 v[66:81], v[172:175], v[180:183], v[66:81]
	ds_read_b128 v[160:163], v32 offset:6144
	ds_read_b128 v[164:167], v141 offset:0
	v_mfma_f32_32x32x16_bf16 v[50:65], v[168:171], v[184:187], v[50:65]
	v_mfma_f32_32x32x16_bf16 v[34:49], v[172:175], v[184:187], v[34:49]
	v_mfma_f32_32x32x16_bf16 v[16:31], v[168:171], v[188:191], v[16:31]
	v_mfma_f32_32x32x16_bf16 v[0:15], v[172:175], v[188:191], v[0:15]
	v_mfma_f32_32x32x16_bf16 v[114:129], v[168:171], v[176:179], v[114:129]
	ds_read_b128 v[168:171], v141 offset:2048
	ds_read_b128 v[172:175], v131 offset:0
	ds_read_b128 v[176:179], v131 offset:2048
	ds_read_b128 v[180:183], v131 offset:4096
	ds_read_b128 v[184:187], v131 offset:6144
	s_waitcnt lgkmcnt(6)
	s_nop 0
	v_mfma_f32_32x32x16_bf16 v[98:113], v[136:139], v[148:151], v[98:113]
	v_mfma_f32_32x32x16_bf16 v[82:97], v[132:135], v[152:155], v[82:97]
	v_mfma_f32_32x32x16_bf16 v[66:81], v[136:139], v[152:155], v[66:81]
	v_mfma_f32_32x32x16_bf16 v[50:65], v[132:135], v[156:159], v[50:65]
	v_mfma_f32_32x32x16_bf16 v[34:49], v[136:139], v[156:159], v[34:49]
	v_mfma_f32_32x32x16_bf16 v[16:31], v[132:135], v[160:163], v[16:31]
	v_mfma_f32_32x32x16_bf16 v[0:15], v[136:139], v[160:163], v[0:15]
	v_mfma_f32_32x32x16_bf16 v[114:129], v[132:135], v[148:151], v[114:129]
	s_waitcnt lgkmcnt(0)
	v_mul_lo_u32 v135, v145, s68
	v_mfma_f32_32x32x16_bf16 v[114:129], v[164:167], v[172:175], v[114:129]
	v_and_b32_e32 v32, 0xffffff80, v143
	v_add_u32_e32 v132, s20, v32
	v_mad_u32_u24 v32, v146, s69, v135
	v_lshlrev_b32_e32 v131, 4, v144
	v_add_u32_e32 v133, v32, v131
	s_waitcnt lgkmcnt(0)
	s_waitcnt vmcnt(0) lgkmcnt(0)
	v_mfma_f32_32x32x16_bf16 v[98:113], v[168:171], v[172:175], v[98:113]
	s_barrier
	v_and_b32_e32 v134, 15, v143
	v_ashrrev_i32_e32 v131, 31, v130
	s_nop 1
	ds_write_b128 v133, v[114:117]
	ds_write_b128 v133, v[118:121] offset:32
	ds_write_b128 v133, v[122:125] offset:64
	ds_write_b128 v133, v[126:129] offset:96
	s_nop 2
	ds_write_b128 v133, v[98:101] offset:128
	ds_write_b128 v133, v[102:105] offset:160
	ds_write_b128 v133, v[106:109] offset:192
	v_or_b32_e32 v102, v132, v142
	v_lshlrev_b32_e32 v32, 4, v134
	v_ashrrev_i32_e32 v103, 31, v102
	v_lshl_add_u64 v[98:99], v[130:131], 2, s[0:1]
	v_lshl_add_u64 v[98:99], v[98:99], 0, v[32:33]
	v_lshlrev_b64 v[100:101], 12, v[102:103]
	ds_write_b128 v133, v[110:113] offset:224
	v_lshl_add_u64 v[118:119], v[98:99], 0, v[100:101]
	flat_load_dwordx4 v[110:113], v[118:119]
	v_and_b32_e32 v101, 64, v208
	v_xor_b32_e32 v100, 1, v208
	v_add_u32_e32 v101, 64, v101
	v_xor_b32_e32 v104, 2, v208
	v_cmp_lt_i32_e32 vcc, v100, v101
	v_or_b32_e32 v108, v135, v32
	v_xor_b32_e32 v105, 4, v208
	v_cndmask_b32_e32 v32, v208, v100, vcc
	v_cmp_lt_i32_e32 vcc, v104, v101
	v_lshlrev_b32_e32 v106, 2, v32
	v_xor_b32_e32 v107, 8, v208
	v_cndmask_b32_e32 v100, v208, v104, vcc
	v_mad_u32_u24 v104, v142, s69, v108
	ds_read_b128 v[114:117], v104
	v_cmp_lt_i32_e32 vcc, v105, v101
	v_mfma_f32_32x32x16_bf16 v[82:97], v[164:167], v[176:179], v[82:97]
	s_waitcnt vmcnt(0) lgkmcnt(0)
	v_add_f32_e64 v112, v116, v112
	v_add_f32_e64 v113, v117, v113
	v_add_f32_e64 v110, v114, v110
	v_add_f32_e64 v111, v115, v111
	v_cndmask_b32_e32 v104, v208, v105, vcc
	v_lshlrev_b32_e32 v105, 2, v100
	v_mul_f32_e32 v32, v111, v111
	v_mul_f32_e32 v100, v113, v113
	v_fmac_f32_e32 v32, v110, v110
	v_fmac_f32_e32 v100, v112, v112
	v_add_f32_e32 v32, v32, v100
	ds_bpermute_b32 v100, v106, v32
	v_lshlrev_b32_e32 v104, 2, v104
	v_mfma_f32_32x32x16_bf16 v[66:81], v[168:171], v[176:179], v[66:81]
	v_cmp_lt_i32_e32 vcc, v107, v101
	flat_store_dwordx4 v[118:119], v[110:113]
	s_waitcnt lgkmcnt(0)
	v_add_f32_e32 v32, v32, v100
	ds_bpermute_b32 v109, v105, v32
	v_cndmask_b32_e32 v101, v208, v107, vcc
	v_lshlrev_b32_e32 v107, 2, v101
	v_cvt_pk_bf16_f32 v114, v110, v111
	v_mfma_f32_32x32x16_bf16 v[50:65], v[164:167], v[180:183], v[50:65]
	s_waitcnt lgkmcnt(0)
	v_add_f32_e32 v32, v32, v109
	ds_bpermute_b32 v109, v104, v32
	v_mov_b64_e32 v[110:111], s[2:3]
	v_cvt_pk_bf16_f32 v115, v112, v113
	v_mad_i64_i32 v[112:113], s[8:9], v102, s74, v[110:111]
	s_waitcnt lgkmcnt(0)
	v_add_f32_e32 v109, v32, v109
	v_mfma_f32_32x32x16_bf16 v[34:49], v[168:171], v[180:183], v[34:49]
	ds_bpermute_b32 v110, v107, v109
	v_ashrrev_i32_e32 v100, 6, v130
	v_lshl_add_u64 v[112:113], v[130:131], 1, v[112:113]
	v_lshlrev_b32_e32 v32, 3, v134
	v_cmp_eq_u32_e32 vcc, 0, v134
	v_ashrrev_i32_e32 v101, 31, v100
	v_lshl_add_u64 v[112:113], v[112:113], 0, v[32:33]
	v_mfma_f32_32x32x16_bf16 v[16:31], v[164:167], v[184:187], v[16:31]
	flat_store_dwordx2 v[112:113], v[114:115]
	v_mfma_f32_32x32x16_bf16 v[0:15], v[168:171], v[184:187], v[0:15]
	s_and_saveexec_b64 s[8:9], vcc
	s_cbranch_execz .LBB0_1318
	v_lshlrev_b64 v[102:103], 6, v[102:103]
	v_lshl_add_u64 v[102:103], s[4:5], 0, v[102:103]
	v_lshl_add_u64 v[102:103], v[100:101], 2, v[102:103]
	s_waitcnt lgkmcnt(0)
	v_add_f32_e32 v32, v109, v110
	flat_store_dword v[102:103], v32
